# plus MLP2A and MLP2B: one hand-written 256x256 tile per workgroup (instead of two 256x128) with v_mfma_f32_16x16x32_f16, bias folded into accumulator init, residual/gate epilogue in the 16x16 layout
# baseline (speedup 1.0000x reference)
.LBB0_46:
	s_mov_b64 s[42:43], 0
	s_andn2_b64 vcc, exec, s[26:27]
	s_mov_b64 s[26:27], 0
	s_cbranch_vccnz .LBB0_107
	s_load_dwordx2 s[46:47], s[22:23], 0x110
	s_load_dwordx2 s[24:25], s[22:23], 0x80
	s_mov_b64 s[26:27], -1
	s_waitcnt lgkmcnt(0)
	s_add_u32 s50, s46, 0x1d00000
	s_addc_u32 s51, s47, 0
	s_add_u32 s44, s24, 0x1000
	s_addc_u32 s45, s25, 0
	v_readlane_b32 s24, v236, 15
	s_add_u32 s48, s46, 0x3208000
	v_readlane_b32 s25, v236, 16
	s_addc_u32 s49, s47, 0
	s_and_b64 vcc, exec, s[24:25]
	s_cbranch_vccz .LBB0_68
	v_readlane_b32 s24, v236, 1
	v_readlane_b32 s25, v236, 2
	s_andn2_b64 vcc, exec, s[24:25]
	s_cbranch_vccnz .LBB0_67
	s_add_u32 s26, s46, 0xaa08000
	s_addc_u32 s27, s47, 0
	v_readlane_b32 s24, v236, 0
	s_and_b32 s65, s24, 7
	s_lshr_b32 s32, s24, 6
	s_lshl_b32 s32, s32, 3
	s_or_b32 s65, s65, s32
	s_and_b32 s32, s24, 0x38
	s_lshr_b32 s53, s65, 2
	s_lshl_b32 s53, s53, 6
	s_and_b32 s65, s65, 3
	s_lshl_b32 s65, s65, 1
	s_add_u32 s24, s32, s53
	s_add_u32 s24, s24, s65
	s_branch .LBB0_51

.LBB0_55:
	s_waitcnt lgkmcnt(0)
	s_lshl_b64 s[36:37], s[28:29], 13
	s_add_u32 s36, s36, s34
	s_addc_u32 s37, s37, s35
	s_lshl_b32 s65, s52, 3
	s_sub_i32 s65, s24, s65
	s_lshl_b32 s28, s65, 7
	s_lshl_b32 s65, s28, 13
	s_add_u32 s98, s50, s65
	s_addc_u32 s99, s51, 0
	v_readfirstlane_b32 s65, v200
	s_lshr_b32 s65, s65, 6
	s_lshl_b32 s25, s65, 11
	s_add_u32 s25, s25, 16
	s_lshl_b32 s65, s65, 18
	s_add_u32 s36, s36, s65
	s_addc_u32 s37, s37, 0
	s_add_u32 s98, s98, s65
	s_addc_u32 s99, s99, 0
	v_bfe_u32 v173, v200, 4, 2
	v_sub_u32_e32 v173, 0, v173
	v_and_b32_e32 v173, 3, v173
	v_and_b32_e32 v172, 3, v200
	v_xor_b32_e32 v172, v172, v173
	v_bfe_u32 v173, v200, 2, 4
	v_lshlrev_b32_e32 v173, 13, v173
	v_lshl_or_b32 v170, v172, 4, v173
	v_add_u32_e32 v171, 0x20000, v170
	v_bfe_u32 v172, v200, 2, 2
	v_sub_u32_e32 v172, 0, v172
	v_and_b32_e32 v172, 3, v172
	v_bfe_u32 v173, v200, 4, 2
	v_xor_b32_e32 v172, v172, v173
	v_and_b32_e32 v173, 15, v200
	v_bfe_u32 v174, v200, 8, 1
	v_lshl_or_b32 v174, v174, 7, v173
	v_lshlrev_b32_e32 v174, 6, v174
	v_lshl_or_b32 v164, v172, 4, v174
	v_bfe_u32 v174, v200, 6, 2
	v_lshl_or_b32 v174, v174, 6, v173
	v_lshlrev_b32_e32 v174, 6, v174
	v_lshl_or_b32 v165, v172, 4, v174
	v_add_u32_e32 v165, 0x4000, v165
	v_bfe_u32 v172, v200, 6, 2
	v_bfe_u32 v173, v200, 4, 2
	v_lshlrev_b32_e32 v172, 6, v172
	v_lshl_or_b32 v172, v173, 2, v172
	v_add_u32_e32 v172, s28, v172
	v_lshlrev_b32_e32 v172, 2, v172
	global_load_dwordx4 v[132:135], v172, s[44:45]
	global_load_dwordx4 v[136:139], v172, s[44:45] offset:64
	global_load_dwordx4 v[140:143], v172, s[44:45] offset:128
	global_load_dwordx4 v[144:147], v172, s[44:45] offset:192
	s_mov_b32 s32, s25
	s_mov_b32 m0, s32
	s_nop 0
	global_load_lds_dwordx4 v170, s[36:37]
	s_add_u32 m0, s32, 0x400
	s_nop 0
	global_load_lds_dwordx4 v171, s[36:37]
	s_add_u32 m0, s32, 0x4000
	s_nop 0
	global_load_lds_dwordx4 v170, s[98:99]
	s_add_u32 m0, s32, 0x4400
	s_nop 0
	global_load_lds_dwordx4 v171, s[98:99]
	s_add_u32 s36, s36, 64
	s_addc_u32 s37, s37, 0
	s_add_u32 s98, s98, 64
	s_addc_u32 s99, s99, 0
	s_add_u32 s32, s25, 0x8000
	s_mov_b32 m0, s32
	s_nop 0
	global_load_lds_dwordx4 v170, s[36:37]
	s_add_u32 m0, s32, 0x400
	s_nop 0
	global_load_lds_dwordx4 v171, s[36:37]
	s_add_u32 m0, s32, 0x4000
	s_nop 0
	global_load_lds_dwordx4 v170, s[98:99]
	s_add_u32 m0, s32, 0x4400
	s_nop 0
	global_load_lds_dwordx4 v171, s[98:99]
	s_add_u32 s36, s36, 64
	s_addc_u32 s37, s37, 0
	s_add_u32 s98, s98, 64
	s_addc_u32 s99, s99, 0
	s_add_u32 s32, s25, 0x10000
	s_mov_b32 m0, s32
	s_nop 0
	global_load_lds_dwordx4 v170, s[36:37]
	s_add_u32 m0, s32, 0x400
	s_nop 0
	global_load_lds_dwordx4 v171, s[36:37]
	s_add_u32 m0, s32, 0x4000
	s_nop 0
	global_load_lds_dwordx4 v170, s[98:99]
	s_add_u32 m0, s32, 0x4400
	s_nop 0
	global_load_lds_dwordx4 v171, s[98:99]
	s_add_u32 s36, s36, 64
	s_addc_u32 s37, s37, 0
	s_add_u32 s98, s98, 64
	s_addc_u32 s99, s99, 0
	s_add_u32 s32, s25, 0x18000
	s_mov_b32 m0, s32
	s_nop 0
	global_load_lds_dwordx4 v170, s[36:37]
	s_add_u32 m0, s32, 0x400
	s_nop 0
	global_load_lds_dwordx4 v171, s[36:37]
	s_add_u32 m0, s32, 0x4000
	s_nop 0
	global_load_lds_dwordx4 v170, s[98:99]
	s_add_u32 m0, s32, 0x4400
	s_nop 0
	global_load_lds_dwordx4 v171, s[98:99]
	s_add_u32 s36, s36, 64
	s_addc_u32 s37, s37, 0
	s_add_u32 s98, s98, 64
	s_addc_u32 s99, s99, 0
	s_waitcnt vmcnt(12)
	s_barrier
	v_mov_b32_e32 v4, v132
	v_mov_b32_e32 v5, v133
	v_mov_b32_e32 v6, v134
	v_mov_b32_e32 v7, v135
	v_mov_b32_e32 v8, v136
	v_mov_b32_e32 v9, v137
	v_mov_b32_e32 v10, v138
	v_mov_b32_e32 v11, v139
	v_mov_b32_e32 v12, v140
	v_mov_b32_e32 v13, v141
	v_mov_b32_e32 v14, v142
	v_mov_b32_e32 v15, v143
	v_mov_b32_e32 v16, v144
	v_mov_b32_e32 v17, v145
	v_mov_b32_e32 v18, v146
	v_mov_b32_e32 v19, v147
	v_mov_b32_e32 v20, v132
	v_mov_b32_e32 v21, v133
	v_mov_b32_e32 v22, v134
	v_mov_b32_e32 v23, v135
	v_mov_b32_e32 v24, v136
	v_mov_b32_e32 v25, v137
	v_mov_b32_e32 v26, v138
	v_mov_b32_e32 v27, v139
	v_mov_b32_e32 v28, v140
	v_mov_b32_e32 v29, v141
	v_mov_b32_e32 v30, v142
	v_mov_b32_e32 v31, v143
	v_mov_b32_e32 v32, v144
	v_mov_b32_e32 v33, v145
	v_mov_b32_e32 v34, v146
	v_mov_b32_e32 v35, v147
	v_mov_b32_e32 v36, v132
	v_mov_b32_e32 v37, v133
	v_mov_b32_e32 v38, v134
	v_mov_b32_e32 v39, v135
	v_mov_b32_e32 v40, v136
	v_mov_b32_e32 v41, v137
	v_mov_b32_e32 v42, v138
	v_mov_b32_e32 v43, v139
	v_mov_b32_e32 v44, v140
	v_mov_b32_e32 v45, v141
	v_mov_b32_e32 v46, v142
	v_mov_b32_e32 v47, v143
	v_mov_b32_e32 v48, v144
	v_mov_b32_e32 v49, v145
	v_mov_b32_e32 v50, v146
	v_mov_b32_e32 v51, v147
	v_mov_b32_e32 v52, v132
	v_mov_b32_e32 v53, v133
	v_mov_b32_e32 v54, v134
	v_mov_b32_e32 v55, v135
	v_mov_b32_e32 v56, v136
	v_mov_b32_e32 v57, v137
	v_mov_b32_e32 v58, v138
	v_mov_b32_e32 v59, v139
	v_mov_b32_e32 v60, v140
	v_mov_b32_e32 v61, v141
	v_mov_b32_e32 v62, v142
	v_mov_b32_e32 v63, v143
	v_mov_b32_e32 v64, v144
	v_mov_b32_e32 v65, v145
	v_mov_b32_e32 v66, v146
	v_mov_b32_e32 v67, v147
	v_mov_b32_e32 v68, v132
	v_mov_b32_e32 v69, v133
	v_mov_b32_e32 v70, v134
	v_mov_b32_e32 v71, v135
	v_mov_b32_e32 v72, v136
	v_mov_b32_e32 v73, v137
	v_mov_b32_e32 v74, v138
	v_mov_b32_e32 v75, v139
	v_mov_b32_e32 v76, v140
	v_mov_b32_e32 v77, v141
	v_mov_b32_e32 v78, v142
	v_mov_b32_e32 v79, v143
	v_mov_b32_e32 v80, v144
	v_mov_b32_e32 v81, v145
	v_mov_b32_e32 v82, v146
	v_mov_b32_e32 v83, v147
	v_mov_b32_e32 v84, v132
	v_mov_b32_e32 v85, v133
	v_mov_b32_e32 v86, v134
	v_mov_b32_e32 v87, v135
	v_mov_b32_e32 v88, v136
	v_mov_b32_e32 v89, v137
	v_mov_b32_e32 v90, v138
	v_mov_b32_e32 v91, v139
	v_mov_b32_e32 v92, v140
	v_mov_b32_e32 v93, v141
	v_mov_b32_e32 v94, v142
	v_mov_b32_e32 v95, v143
	v_mov_b32_e32 v96, v144
	v_mov_b32_e32 v97, v145
	v_mov_b32_e32 v98, v146
	v_mov_b32_e32 v99, v147
	v_mov_b32_e32 v100, v132
	v_mov_b32_e32 v101, v133
	v_mov_b32_e32 v102, v134
	v_mov_b32_e32 v103, v135
	v_mov_b32_e32 v104, v136
	v_mov_b32_e32 v105, v137
	v_mov_b32_e32 v106, v138
	v_mov_b32_e32 v107, v139
	v_mov_b32_e32 v108, v140
	v_mov_b32_e32 v109, v141
	v_mov_b32_e32 v110, v142
	v_mov_b32_e32 v111, v143
	v_mov_b32_e32 v112, v144
	v_mov_b32_e32 v113, v145
	v_mov_b32_e32 v114, v146
	v_mov_b32_e32 v115, v147
	v_mov_b32_e32 v116, v132
	v_mov_b32_e32 v117, v133
	v_mov_b32_e32 v118, v134
	v_mov_b32_e32 v119, v135
	v_mov_b32_e32 v120, v136
	v_mov_b32_e32 v121, v137
	v_mov_b32_e32 v122, v138
	v_mov_b32_e32 v123, v139
	v_mov_b32_e32 v124, v140
	v_mov_b32_e32 v125, v141
	v_mov_b32_e32 v126, v142
	v_mov_b32_e32 v127, v143
	v_mov_b32_e32 v128, v144
	v_mov_b32_e32 v129, v145
	v_mov_b32_e32 v130, v146
	v_mov_b32_e32 v131, v147
	s_mov_b32 s31, 0
	s_mov_b32 s53, 0
	s_nop 1
	v_add_u32_e32 v168, s31, v165
	v_add_u32_e32 v169, s31, v164
	ds_read_b128 v[132:135], v168 offset:16
	ds_read_b128 v[136:139], v168 offset:1040
	ds_read_b128 v[140:143], v168 offset:2064
	ds_read_b128 v[144:147], v168 offset:3088
	ds_read_b128 v[184:187], v169 offset:16
	ds_read_b128 v[188:191], v169 offset:1040
	ds_read_b128 v[192:195], v169 offset:2064
	ds_read_b128 v[196:199], v169 offset:3088
	s_waitcnt lgkmcnt(0)
.Lt_mlp2b:
	v_add_u32_e32 v169, s31, v164
	v_mfma_f32_16x16x32_f16 v[4:7], v[132:135], v[184:187], v[4:7]
	ds_read_b128 v[238:241], v169 offset:4112
	v_mfma_f32_16x16x32_f16 v[8:11], v[136:139], v[184:187], v[8:11]
	ds_read_b128 v[242:245], v169 offset:5136
	v_mfma_f32_16x16x32_f16 v[12:15], v[140:143], v[184:187], v[12:15]
	ds_read_b128 v[246:249], v169 offset:6160
	v_mfma_f32_16x16x32_f16 v[16:19], v[144:147], v[184:187], v[16:19]
	ds_read_b128 v[250:253], v169 offset:7184
	v_mfma_f32_16x16x32_f16 v[20:23], v[132:135], v[188:191], v[20:23]
	v_mfma_f32_16x16x32_f16 v[24:27], v[136:139], v[188:191], v[24:27]
	v_mfma_f32_16x16x32_f16 v[28:31], v[140:143], v[188:191], v[28:31]
	v_mfma_f32_16x16x32_f16 v[32:35], v[144:147], v[188:191], v[32:35]
	v_mfma_f32_16x16x32_f16 v[36:39], v[132:135], v[192:195], v[36:39]
	v_mfma_f32_16x16x32_f16 v[40:43], v[136:139], v[192:195], v[40:43]
	v_mfma_f32_16x16x32_f16 v[44:47], v[140:143], v[192:195], v[44:47]
	v_mfma_f32_16x16x32_f16 v[48:51], v[144:147], v[192:195], v[48:51]
	v_mfma_f32_16x16x32_f16 v[52:55], v[132:135], v[196:199], v[52:55]
	v_mfma_f32_16x16x32_f16 v[56:59], v[136:139], v[196:199], v[56:59]
	v_mfma_f32_16x16x32_f16 v[60:63], v[140:143], v[196:199], v[60:63]
	v_mfma_f32_16x16x32_f16 v[64:67], v[144:147], v[196:199], v[64:67]
	s_waitcnt vmcnt(8) lgkmcnt(0)
	s_barrier
	s_add_i32 s32, s31, 0x8000
	s_cmp_lg_u32 s31, 0x18000
	s_cselect_b32 s32, s32, 0
	v_add_u32_e32 v168, s32, v165
	v_add_u32_e32 v169, s32, v164
	s_add_u32 vcc_lo, s25, s31
	v_mfma_f32_16x16x32_f16 v[68:71], v[132:135], v[238:241], v[68:71]
	ds_read_b128 v[148:151], v168 offset:16
	ds_read_b128 v[184:187], v169 offset:16
	v_mfma_f32_16x16x32_f16 v[72:75], v[136:139], v[238:241], v[72:75]
	ds_read_b128 v[152:155], v168 offset:1040
	ds_read_b128 v[188:191], v169 offset:1040
	v_mfma_f32_16x16x32_f16 v[76:79], v[140:143], v[238:241], v[76:79]
	ds_read_b128 v[156:159], v168 offset:2064
	ds_read_b128 v[192:195], v169 offset:2064
	v_mfma_f32_16x16x32_f16 v[80:83], v[144:147], v[238:241], v[80:83]
	ds_read_b128 v[160:163], v168 offset:3088
	ds_read_b128 v[196:199], v169 offset:3088
	v_mfma_f32_16x16x32_f16 v[84:87], v[132:135], v[242:245], v[84:87]
	v_mfma_f32_16x16x32_f16 v[88:91], v[136:139], v[242:245], v[88:91]
	v_mfma_f32_16x16x32_f16 v[92:95], v[140:143], v[242:245], v[92:95]
	v_mfma_f32_16x16x32_f16 v[96:99], v[144:147], v[242:245], v[96:99]
	v_mfma_f32_16x16x32_f16 v[100:103], v[132:135], v[246:249], v[100:103]
	s_mov_b32 m0, vcc_lo
	s_nop 0
	global_load_lds_dwordx4 v170, s[36:37]
	v_mfma_f32_16x16x32_f16 v[104:107], v[136:139], v[246:249], v[104:107]
	s_add_u32 m0, vcc_lo, 0x400
	s_nop 0
	global_load_lds_dwordx4 v171, s[36:37]
	v_mfma_f32_16x16x32_f16 v[108:111], v[140:143], v[246:249], v[108:111]
	s_add_u32 m0, vcc_lo, 0x4000
	s_nop 0
	global_load_lds_dwordx4 v170, s[98:99]
	v_mfma_f32_16x16x32_f16 v[112:115], v[144:147], v[246:249], v[112:115]
	s_add_u32 m0, vcc_lo, 0x4400
	s_nop 0
	global_load_lds_dwordx4 v171, s[98:99]
	v_mfma_f32_16x16x32_f16 v[116:119], v[132:135], v[250:253], v[116:119]
	v_mfma_f32_16x16x32_f16 v[120:123], v[136:139], v[250:253], v[120:123]
	v_mfma_f32_16x16x32_f16 v[124:127], v[140:143], v[250:253], v[124:127]
	v_mfma_f32_16x16x32_f16 v[128:131], v[144:147], v[250:253], v[128:131]
	s_waitcnt lgkmcnt(0)
	s_mov_b32 s31, s32
	s_add_u32 s36, s36, 64
	s_addc_u32 s37, s37, 0
	s_add_u32 s98, s98, 64
	s_addc_u32 s99, s99, 0
	v_add_u32_e32 v169, s31, v164
	v_mfma_f32_16x16x32_f16 v[4:7], v[148:151], v[184:187], v[4:7]
	ds_read_b128 v[238:241], v169 offset:4112
	v_mfma_f32_16x16x32_f16 v[8:11], v[152:155], v[184:187], v[8:11]
	ds_read_b128 v[242:245], v169 offset:5136
	v_mfma_f32_16x16x32_f16 v[12:15], v[156:159], v[184:187], v[12:15]
	ds_read_b128 v[246:249], v169 offset:6160
	v_mfma_f32_16x16x32_f16 v[16:19], v[160:163], v[184:187], v[16:19]
	ds_read_b128 v[250:253], v169 offset:7184
	v_mfma_f32_16x16x32_f16 v[20:23], v[148:151], v[188:191], v[20:23]
	v_mfma_f32_16x16x32_f16 v[24:27], v[152:155], v[188:191], v[24:27]
	v_mfma_f32_16x16x32_f16 v[28:31], v[156:159], v[188:191], v[28:31]
	v_mfma_f32_16x16x32_f16 v[32:35], v[160:163], v[188:191], v[32:35]
	v_mfma_f32_16x16x32_f16 v[36:39], v[148:151], v[192:195], v[36:39]
	v_mfma_f32_16x16x32_f16 v[40:43], v[152:155], v[192:195], v[40:43]
	v_mfma_f32_16x16x32_f16 v[44:47], v[156:159], v[192:195], v[44:47]
	v_mfma_f32_16x16x32_f16 v[48:51], v[160:163], v[192:195], v[48:51]
	v_mfma_f32_16x16x32_f16 v[52:55], v[148:151], v[196:199], v[52:55]
	v_mfma_f32_16x16x32_f16 v[56:59], v[152:155], v[196:199], v[56:59]
	v_mfma_f32_16x16x32_f16 v[60:63], v[156:159], v[196:199], v[60:63]
	v_mfma_f32_16x16x32_f16 v[64:67], v[160:163], v[196:199], v[64:67]
	s_waitcnt vmcnt(8) lgkmcnt(0)
	s_barrier
	s_add_i32 s32, s31, 0x8000
	s_cmp_lg_u32 s31, 0x18000
	s_cselect_b32 s32, s32, 0
	v_add_u32_e32 v168, s32, v165
	v_add_u32_e32 v169, s32, v164
	s_add_u32 vcc_lo, s25, s31
	v_mfma_f32_16x16x32_f16 v[68:71], v[148:151], v[238:241], v[68:71]
	ds_read_b128 v[132:135], v168 offset:16
	ds_read_b128 v[184:187], v169 offset:16
	v_mfma_f32_16x16x32_f16 v[72:75], v[152:155], v[238:241], v[72:75]
	ds_read_b128 v[136:139], v168 offset:1040
	ds_read_b128 v[188:191], v169 offset:1040
	v_mfma_f32_16x16x32_f16 v[76:79], v[156:159], v[238:241], v[76:79]
	ds_read_b128 v[140:143], v168 offset:2064
	ds_read_b128 v[192:195], v169 offset:2064
	v_mfma_f32_16x16x32_f16 v[80:83], v[160:163], v[238:241], v[80:83]
	ds_read_b128 v[144:147], v168 offset:3088
	ds_read_b128 v[196:199], v169 offset:3088
	v_mfma_f32_16x16x32_f16 v[84:87], v[148:151], v[242:245], v[84:87]
	v_mfma_f32_16x16x32_f16 v[88:91], v[152:155], v[242:245], v[88:91]
	v_mfma_f32_16x16x32_f16 v[92:95], v[156:159], v[242:245], v[92:95]
	v_mfma_f32_16x16x32_f16 v[96:99], v[160:163], v[242:245], v[96:99]
	v_mfma_f32_16x16x32_f16 v[100:103], v[148:151], v[246:249], v[100:103]
	s_mov_b32 m0, vcc_lo
	s_nop 0
	global_load_lds_dwordx4 v170, s[36:37]
	v_mfma_f32_16x16x32_f16 v[104:107], v[152:155], v[246:249], v[104:107]
	s_add_u32 m0, vcc_lo, 0x400
	s_nop 0
	global_load_lds_dwordx4 v171, s[36:37]
	v_mfma_f32_16x16x32_f16 v[108:111], v[156:159], v[246:249], v[108:111]
	s_add_u32 m0, vcc_lo, 0x4000
	s_nop 0
	global_load_lds_dwordx4 v170, s[98:99]
	v_mfma_f32_16x16x32_f16 v[112:115], v[160:163], v[246:249], v[112:115]
	s_add_u32 m0, vcc_lo, 0x4400
	s_nop 0
	global_load_lds_dwordx4 v171, s[98:99]
	v_mfma_f32_16x16x32_f16 v[116:119], v[148:151], v[250:253], v[116:119]
	v_mfma_f32_16x16x32_f16 v[120:123], v[152:155], v[250:253], v[120:123]
	v_mfma_f32_16x16x32_f16 v[124:127], v[156:159], v[250:253], v[124:127]
	v_mfma_f32_16x16x32_f16 v[128:131], v[160:163], v[250:253], v[128:131]
	s_waitcnt lgkmcnt(0)
	s_mov_b32 s31, s32
	s_add_u32 s36, s36, 64
	s_addc_u32 s37, s37, 0
	s_add_u32 s98, s98, 64
	s_addc_u32 s99, s99, 0
	s_add_i32 s53, s53, 2
	s_cmp_lt_u32 s53, 124
	s_cbranch_scc1 .Lt_mlp2b
	v_add_u32_e32 v169, s31, v164
	v_mfma_f32_16x16x32_f16 v[4:7], v[132:135], v[184:187], v[4:7]
	ds_read_b128 v[238:241], v169 offset:4112
	v_mfma_f32_16x16x32_f16 v[8:11], v[136:139], v[184:187], v[8:11]
	ds_read_b128 v[242:245], v169 offset:5136
	v_mfma_f32_16x16x32_f16 v[12:15], v[140:143], v[184:187], v[12:15]
	ds_read_b128 v[246:249], v169 offset:6160
	v_mfma_f32_16x16x32_f16 v[16:19], v[144:147], v[184:187], v[16:19]
	ds_read_b128 v[250:253], v169 offset:7184
	v_mfma_f32_16x16x32_f16 v[20:23], v[132:135], v[188:191], v[20:23]
	v_mfma_f32_16x16x32_f16 v[24:27], v[136:139], v[188:191], v[24:27]
	v_mfma_f32_16x16x32_f16 v[28:31], v[140:143], v[188:191], v[28:31]
	v_mfma_f32_16x16x32_f16 v[32:35], v[144:147], v[188:191], v[32:35]
	v_mfma_f32_16x16x32_f16 v[36:39], v[132:135], v[192:195], v[36:39]
	v_mfma_f32_16x16x32_f16 v[40:43], v[136:139], v[192:195], v[40:43]
	v_mfma_f32_16x16x32_f16 v[44:47], v[140:143], v[192:195], v[44:47]
	v_mfma_f32_16x16x32_f16 v[48:51], v[144:147], v[192:195], v[48:51]
	v_mfma_f32_16x16x32_f16 v[52:55], v[132:135], v[196:199], v[52:55]
	v_mfma_f32_16x16x32_f16 v[56:59], v[136:139], v[196:199], v[56:59]
	v_mfma_f32_16x16x32_f16 v[60:63], v[140:143], v[196:199], v[60:63]
	v_mfma_f32_16x16x32_f16 v[64:67], v[144:147], v[196:199], v[64:67]
	s_waitcnt vmcnt(8) lgkmcnt(0)
	s_barrier
	s_add_i32 s32, s31, 0x8000
	s_cmp_lg_u32 s31, 0x18000
	s_cselect_b32 s32, s32, 0
	v_add_u32_e32 v168, s32, v165
	v_add_u32_e32 v169, s32, v164
	v_mfma_f32_16x16x32_f16 v[68:71], v[132:135], v[238:241], v[68:71]
	ds_read_b128 v[148:151], v168 offset:16
	ds_read_b128 v[184:187], v169 offset:16
	v_mfma_f32_16x16x32_f16 v[72:75], v[136:139], v[238:241], v[72:75]
	ds_read_b128 v[152:155], v168 offset:1040
	ds_read_b128 v[188:191], v169 offset:1040
	v_mfma_f32_16x16x32_f16 v[76:79], v[140:143], v[238:241], v[76:79]
	ds_read_b128 v[156:159], v168 offset:2064
	ds_read_b128 v[192:195], v169 offset:2064
	v_mfma_f32_16x16x32_f16 v[80:83], v[144:147], v[238:241], v[80:83]
	ds_read_b128 v[160:163], v168 offset:3088
	ds_read_b128 v[196:199], v169 offset:3088
	v_mfma_f32_16x16x32_f16 v[84:87], v[132:135], v[242:245], v[84:87]
	v_mfma_f32_16x16x32_f16 v[88:91], v[136:139], v[242:245], v[88:91]
	v_mfma_f32_16x16x32_f16 v[92:95], v[140:143], v[242:245], v[92:95]
	v_mfma_f32_16x16x32_f16 v[96:99], v[144:147], v[242:245], v[96:99]
	v_mfma_f32_16x16x32_f16 v[100:103], v[132:135], v[246:249], v[100:103]
	v_mfma_f32_16x16x32_f16 v[104:107], v[136:139], v[246:249], v[104:107]
	v_mfma_f32_16x16x32_f16 v[108:111], v[140:143], v[246:249], v[108:111]
	v_mfma_f32_16x16x32_f16 v[112:115], v[144:147], v[246:249], v[112:115]
	v_mfma_f32_16x16x32_f16 v[116:119], v[132:135], v[250:253], v[116:119]
	v_mfma_f32_16x16x32_f16 v[120:123], v[136:139], v[250:253], v[120:123]
	v_mfma_f32_16x16x32_f16 v[124:127], v[140:143], v[250:253], v[124:127]
	v_mfma_f32_16x16x32_f16 v[128:131], v[144:147], v[250:253], v[128:131]
	s_waitcnt lgkmcnt(0)
	s_mov_b32 s31, s32
	v_add_u32_e32 v169, s31, v164
	v_mfma_f32_16x16x32_f16 v[4:7], v[148:151], v[184:187], v[4:7]
	ds_read_b128 v[238:241], v169 offset:4112
	v_mfma_f32_16x16x32_f16 v[8:11], v[152:155], v[184:187], v[8:11]
	ds_read_b128 v[242:245], v169 offset:5136
	v_mfma_f32_16x16x32_f16 v[12:15], v[156:159], v[184:187], v[12:15]
	ds_read_b128 v[246:249], v169 offset:6160
	v_mfma_f32_16x16x32_f16 v[16:19], v[160:163], v[184:187], v[16:19]
	ds_read_b128 v[250:253], v169 offset:7184
	v_mfma_f32_16x16x32_f16 v[20:23], v[148:151], v[188:191], v[20:23]
	v_mfma_f32_16x16x32_f16 v[24:27], v[152:155], v[188:191], v[24:27]
	v_mfma_f32_16x16x32_f16 v[28:31], v[156:159], v[188:191], v[28:31]
	v_mfma_f32_16x16x32_f16 v[32:35], v[160:163], v[188:191], v[32:35]
	v_mfma_f32_16x16x32_f16 v[36:39], v[148:151], v[192:195], v[36:39]
	v_mfma_f32_16x16x32_f16 v[40:43], v[152:155], v[192:195], v[40:43]
	v_mfma_f32_16x16x32_f16 v[44:47], v[156:159], v[192:195], v[44:47]
	v_mfma_f32_16x16x32_f16 v[48:51], v[160:163], v[192:195], v[48:51]
	v_mfma_f32_16x16x32_f16 v[52:55], v[148:151], v[196:199], v[52:55]
	v_mfma_f32_16x16x32_f16 v[56:59], v[152:155], v[196:199], v[56:59]
	v_mfma_f32_16x16x32_f16 v[60:63], v[156:159], v[196:199], v[60:63]
	v_mfma_f32_16x16x32_f16 v[64:67], v[160:163], v[196:199], v[64:67]
	s_waitcnt vmcnt(4) lgkmcnt(0)
	s_barrier
	s_add_i32 s32, s31, 0x8000
	s_cmp_lg_u32 s31, 0x18000
	s_cselect_b32 s32, s32, 0
	v_add_u32_e32 v168, s32, v165
	v_add_u32_e32 v169, s32, v164
	v_mfma_f32_16x16x32_f16 v[68:71], v[148:151], v[238:241], v[68:71]
	ds_read_b128 v[132:135], v168 offset:16
	ds_read_b128 v[184:187], v169 offset:16
	v_mfma_f32_16x16x32_f16 v[72:75], v[152:155], v[238:241], v[72:75]
	ds_read_b128 v[136:139], v168 offset:1040
	ds_read_b128 v[188:191], v169 offset:1040
	v_mfma_f32_16x16x32_f16 v[76:79], v[156:159], v[238:241], v[76:79]
	ds_read_b128 v[140:143], v168 offset:2064
	ds_read_b128 v[192:195], v169 offset:2064
	v_mfma_f32_16x16x32_f16 v[80:83], v[160:163], v[238:241], v[80:83]
	ds_read_b128 v[144:147], v168 offset:3088
	ds_read_b128 v[196:199], v169 offset:3088
	v_mfma_f32_16x16x32_f16 v[84:87], v[148:151], v[242:245], v[84:87]
	v_mfma_f32_16x16x32_f16 v[88:91], v[152:155], v[242:245], v[88:91]
	v_mfma_f32_16x16x32_f16 v[92:95], v[156:159], v[242:245], v[92:95]
	v_mfma_f32_16x16x32_f16 v[96:99], v[160:163], v[242:245], v[96:99]
	v_mfma_f32_16x16x32_f16 v[100:103], v[148:151], v[246:249], v[100:103]
	v_mfma_f32_16x16x32_f16 v[104:107], v[152:155], v[246:249], v[104:107]
	v_mfma_f32_16x16x32_f16 v[108:111], v[156:159], v[246:249], v[108:111]
	v_mfma_f32_16x16x32_f16 v[112:115], v[160:163], v[246:249], v[112:115]
	v_mfma_f32_16x16x32_f16 v[116:119], v[148:151], v[250:253], v[116:119]
	v_mfma_f32_16x16x32_f16 v[120:123], v[152:155], v[250:253], v[120:123]
	v_mfma_f32_16x16x32_f16 v[124:127], v[156:159], v[250:253], v[124:127]
	v_mfma_f32_16x16x32_f16 v[128:131], v[160:163], v[250:253], v[128:131]
	s_waitcnt lgkmcnt(0)
	s_mov_b32 s31, s32
	v_add_u32_e32 v169, s31, v164
	v_mfma_f32_16x16x32_f16 v[4:7], v[132:135], v[184:187], v[4:7]
	ds_read_b128 v[238:241], v169 offset:4112
	v_mfma_f32_16x16x32_f16 v[8:11], v[136:139], v[184:187], v[8:11]
	ds_read_b128 v[242:245], v169 offset:5136
	v_mfma_f32_16x16x32_f16 v[12:15], v[140:143], v[184:187], v[12:15]
	ds_read_b128 v[246:249], v169 offset:6160
	v_mfma_f32_16x16x32_f16 v[16:19], v[144:147], v[184:187], v[16:19]
	ds_read_b128 v[250:253], v169 offset:7184
	v_mfma_f32_16x16x32_f16 v[20:23], v[132:135], v[188:191], v[20:23]
	v_mfma_f32_16x16x32_f16 v[24:27], v[136:139], v[188:191], v[24:27]
	v_mfma_f32_16x16x32_f16 v[28:31], v[140:143], v[188:191], v[28:31]
	v_mfma_f32_16x16x32_f16 v[32:35], v[144:147], v[188:191], v[32:35]
	v_mfma_f32_16x16x32_f16 v[36:39], v[132:135], v[192:195], v[36:39]
	v_mfma_f32_16x16x32_f16 v[40:43], v[136:139], v[192:195], v[40:43]
	v_mfma_f32_16x16x32_f16 v[44:47], v[140:143], v[192:195], v[44:47]
	v_mfma_f32_16x16x32_f16 v[48:51], v[144:147], v[192:195], v[48:51]
	v_mfma_f32_16x16x32_f16 v[52:55], v[132:135], v[196:199], v[52:55]
	v_mfma_f32_16x16x32_f16 v[56:59], v[136:139], v[196:199], v[56:59]
	v_mfma_f32_16x16x32_f16 v[60:63], v[140:143], v[196:199], v[60:63]
	v_mfma_f32_16x16x32_f16 v[64:67], v[144:147], v[196:199], v[64:67]
	s_waitcnt vmcnt(0) lgkmcnt(0)
	s_barrier
	s_add_i32 s32, s31, 0x8000
	s_cmp_lg_u32 s31, 0x18000
	s_cselect_b32 s32, s32, 0
	v_add_u32_e32 v168, s32, v165
	v_add_u32_e32 v169, s32, v164
	v_mfma_f32_16x16x32_f16 v[68:71], v[132:135], v[238:241], v[68:71]
	ds_read_b128 v[148:151], v168 offset:16
	ds_read_b128 v[184:187], v169 offset:16
	v_mfma_f32_16x16x32_f16 v[72:75], v[136:139], v[238:241], v[72:75]
	ds_read_b128 v[152:155], v168 offset:1040
	ds_read_b128 v[188:191], v169 offset:1040
	v_mfma_f32_16x16x32_f16 v[76:79], v[140:143], v[238:241], v[76:79]
	ds_read_b128 v[156:159], v168 offset:2064
	ds_read_b128 v[192:195], v169 offset:2064
	v_mfma_f32_16x16x32_f16 v[80:83], v[144:147], v[238:241], v[80:83]
	ds_read_b128 v[160:163], v168 offset:3088
	ds_read_b128 v[196:199], v169 offset:3088
	v_mfma_f32_16x16x32_f16 v[84:87], v[132:135], v[242:245], v[84:87]
	v_mfma_f32_16x16x32_f16 v[88:91], v[136:139], v[242:245], v[88:91]
	v_mfma_f32_16x16x32_f16 v[92:95], v[140:143], v[242:245], v[92:95]
	v_mfma_f32_16x16x32_f16 v[96:99], v[144:147], v[242:245], v[96:99]
	v_mfma_f32_16x16x32_f16 v[100:103], v[132:135], v[246:249], v[100:103]
	v_mfma_f32_16x16x32_f16 v[104:107], v[136:139], v[246:249], v[104:107]
	v_mfma_f32_16x16x32_f16 v[108:111], v[140:143], v[246:249], v[108:111]
	v_mfma_f32_16x16x32_f16 v[112:115], v[144:147], v[246:249], v[112:115]
	v_mfma_f32_16x16x32_f16 v[116:119], v[132:135], v[250:253], v[116:119]
	v_mfma_f32_16x16x32_f16 v[120:123], v[136:139], v[250:253], v[120:123]
	v_mfma_f32_16x16x32_f16 v[124:127], v[140:143], v[250:253], v[124:127]
	v_mfma_f32_16x16x32_f16 v[128:131], v[144:147], v[250:253], v[128:131]
	s_waitcnt lgkmcnt(0)
	s_mov_b32 s31, s32
	v_add_u32_e32 v169, s31, v164
	v_mfma_f32_16x16x32_f16 v[4:7], v[148:151], v[184:187], v[4:7]
	ds_read_b128 v[238:241], v169 offset:4112
	v_mfma_f32_16x16x32_f16 v[8:11], v[152:155], v[184:187], v[8:11]
	ds_read_b128 v[242:245], v169 offset:5136
	v_mfma_f32_16x16x32_f16 v[12:15], v[156:159], v[184:187], v[12:15]
	ds_read_b128 v[246:249], v169 offset:6160
	v_mfma_f32_16x16x32_f16 v[16:19], v[160:163], v[184:187], v[16:19]
	ds_read_b128 v[250:253], v169 offset:7184
	v_mfma_f32_16x16x32_f16 v[20:23], v[148:151], v[188:191], v[20:23]
	v_mfma_f32_16x16x32_f16 v[24:27], v[152:155], v[188:191], v[24:27]
	v_mfma_f32_16x16x32_f16 v[28:31], v[156:159], v[188:191], v[28:31]
	v_mfma_f32_16x16x32_f16 v[32:35], v[160:163], v[188:191], v[32:35]
	v_mfma_f32_16x16x32_f16 v[36:39], v[148:151], v[192:195], v[36:39]
	v_mfma_f32_16x16x32_f16 v[40:43], v[152:155], v[192:195], v[40:43]
	v_mfma_f32_16x16x32_f16 v[44:47], v[156:159], v[192:195], v[44:47]
	v_mfma_f32_16x16x32_f16 v[48:51], v[160:163], v[192:195], v[48:51]
	v_mfma_f32_16x16x32_f16 v[52:55], v[148:151], v[196:199], v[52:55]
	v_mfma_f32_16x16x32_f16 v[56:59], v[152:155], v[196:199], v[56:59]
	v_mfma_f32_16x16x32_f16 v[60:63], v[156:159], v[196:199], v[60:63]
	v_mfma_f32_16x16x32_f16 v[64:67], v[160:163], v[196:199], v[64:67]
	s_waitcnt lgkmcnt(0)
	s_barrier
	v_mfma_f32_16x16x32_f16 v[68:71], v[148:151], v[238:241], v[68:71]
	v_mfma_f32_16x16x32_f16 v[72:75], v[152:155], v[238:241], v[72:75]
	v_mfma_f32_16x16x32_f16 v[76:79], v[156:159], v[238:241], v[76:79]
	v_mfma_f32_16x16x32_f16 v[80:83], v[160:163], v[238:241], v[80:83]
	v_mfma_f32_16x16x32_f16 v[84:87], v[148:151], v[242:245], v[84:87]
	v_mfma_f32_16x16x32_f16 v[88:91], v[152:155], v[242:245], v[88:91]
	v_mfma_f32_16x16x32_f16 v[92:95], v[156:159], v[242:245], v[92:95]
	v_mfma_f32_16x16x32_f16 v[96:99], v[160:163], v[242:245], v[96:99]
	v_mfma_f32_16x16x32_f16 v[100:103], v[148:151], v[246:249], v[100:103]
	v_mfma_f32_16x16x32_f16 v[104:107], v[152:155], v[246:249], v[104:107]
	v_mfma_f32_16x16x32_f16 v[108:111], v[156:159], v[246:249], v[108:111]
	v_mfma_f32_16x16x32_f16 v[112:115], v[160:163], v[246:249], v[112:115]
	v_mfma_f32_16x16x32_f16 v[116:119], v[148:151], v[250:253], v[116:119]
	v_mfma_f32_16x16x32_f16 v[120:123], v[152:155], v[250:253], v[120:123]
	v_mfma_f32_16x16x32_f16 v[124:127], v[156:159], v[250:253], v[124:127]
	v_mfma_f32_16x16x32_f16 v[128:131], v[160:163], v[250:253], v[128:131]
	s_sub_u32 s77, s30, 0x1000
	s_lshr_b32 s77, s77, 12
	s_add_u32 s77, s77, 1
	s_cmp_lt_u32 s30, 0x1000
	s_cselect_b32 s77, 0, s77
	s_mul_i32 s77, s77, 0x6000
	s_add_u32 s68, s46, s77
	s_addc_u32 s69, s47, 0
	s_add_u32 s68, s68, 0xfa2e600
	s_addc_u32 s69, s69, 0
	s_lshl_b32 s82, s30, 11
	s_add_u32 s80, s48, s82
	s_addc_u32 s81, s49, 0
	s_lshl_b32 s82, s28, 1
	s_add_u32 s80, s80, s82
	s_addc_u32 s81, s81, 0
	v_and_b32_e32 v172, 15, v200
	v_bfe_u32 v173, v200, 4, 2
	v_bfe_u32 v174, v200, 6, 2
	v_bfe_u32 v175, v200, 8, 1
	v_lshlrev_b32_e32 v176, 6, v174
	v_lshl_or_b32 v176, v173, 2, v176
	v_lshl_or_b32 v175, v175, 7, v172
	v_lshlrev_b32_e32 v175, 11, v175
	v_lshl_add_u32 v177, v176, 1, v175
	v_add_u32_e32 v176, s28, v176
	v_lshlrev_b32_e32 v176, 2, v176
	global_load_dwordx4 v[132:135], v176, s[68:69]
	global_load_dwordx4 v[136:139], v176, s[68:69] offset:64
	global_load_dwordx4 v[140:143], v176, s[68:69] offset:128
	global_load_dwordx4 v[144:147], v176, s[68:69] offset:192
	v_mov_b32_e32 v178, v177
	global_load_dwordx2 v[184:185], v178, s[80:81]
	global_load_dwordx2 v[186:187], v178, s[80:81] offset:32
	global_load_dwordx2 v[188:189], v178, s[80:81] offset:64
	global_load_dwordx2 v[190:191], v178, s[80:81] offset:96
	v_add_u32_e32 v178, 0x8000, v178
	global_load_dwordx2 v[238:239], v178, s[80:81]
	global_load_dwordx2 v[240:241], v178, s[80:81] offset:32
	global_load_dwordx2 v[242:243], v178, s[80:81] offset:64
	global_load_dwordx2 v[244:245], v178, s[80:81] offset:96
	s_waitcnt vmcnt(7)
	v_cvt_f32_f16_e32 v164, v184
	v_cvt_f32_f16_sdwa v165, v184 dst_sel:DWORD dst_unused:UNUSED_PAD src0_sel:WORD_1
	v_cvt_f32_f16_e32 v166, v185
	v_cvt_f32_f16_sdwa v167, v185 dst_sel:DWORD dst_unused:UNUSED_PAD src0_sel:WORD_1
	v_pk_mul_f32 v[164:165], v[164:165], s[84:85] op_sel_hi:[1,0]
	v_pk_mul_f32 v[166:167], v[166:167], s[84:85] op_sel_hi:[1,0]
	v_pk_fma_f32 v[4:5], v[4:5], v[132:133], v[164:165]
	v_pk_fma_f32 v[6:7], v[6:7], v[134:135], v[166:167]
	v_cvt_pk_f16_f32 v172, v4, v5
	v_cvt_pk_f16_f32 v173, v6, v7
	global_store_dwordx2 v177, v[172:173], s[80:81]
	s_waitcnt vmcnt(7)
	v_cvt_f32_f16_e32 v164, v186
	v_cvt_f32_f16_sdwa v165, v186 dst_sel:DWORD dst_unused:UNUSED_PAD src0_sel:WORD_1
	v_cvt_f32_f16_e32 v166, v187
	v_cvt_f32_f16_sdwa v167, v187 dst_sel:DWORD dst_unused:UNUSED_PAD src0_sel:WORD_1
	v_pk_mul_f32 v[164:165], v[164:165], s[84:85] op_sel_hi:[1,0]
	v_pk_mul_f32 v[166:167], v[166:167], s[84:85] op_sel_hi:[1,0]
	v_pk_fma_f32 v[8:9], v[8:9], v[136:137], v[164:165]
	v_pk_fma_f32 v[10:11], v[10:11], v[138:139], v[166:167]
	v_cvt_pk_f16_f32 v174, v8, v9
	v_cvt_pk_f16_f32 v175, v10, v11
	global_store_dwordx2 v177, v[174:175], s[80:81] offset:32
	s_waitcnt vmcnt(7)
	v_cvt_f32_f16_e32 v164, v188
	v_cvt_f32_f16_sdwa v165, v188 dst_sel:DWORD dst_unused:UNUSED_PAD src0_sel:WORD_1
	v_cvt_f32_f16_e32 v166, v189
	v_cvt_f32_f16_sdwa v167, v189 dst_sel:DWORD dst_unused:UNUSED_PAD src0_sel:WORD_1
	v_pk_mul_f32 v[164:165], v[164:165], s[84:85] op_sel_hi:[1,0]
	v_pk_mul_f32 v[166:167], v[166:167], s[84:85] op_sel_hi:[1,0]
	v_pk_fma_f32 v[12:13], v[12:13], v[140:141], v[164:165]
	v_pk_fma_f32 v[14:15], v[14:15], v[142:143], v[166:167]
	v_cvt_pk_f16_f32 v172, v12, v13
	v_cvt_pk_f16_f32 v173, v14, v15
	global_store_dwordx2 v177, v[172:173], s[80:81] offset:64
	s_waitcnt vmcnt(7)
	v_cvt_f32_f16_e32 v164, v190
	v_cvt_f32_f16_sdwa v165, v190 dst_sel:DWORD dst_unused:UNUSED_PAD src0_sel:WORD_1
	v_cvt_f32_f16_e32 v166, v191
	v_cvt_f32_f16_sdwa v167, v191 dst_sel:DWORD dst_unused:UNUSED_PAD src0_sel:WORD_1
	v_pk_mul_f32 v[164:165], v[164:165], s[84:85] op_sel_hi:[1,0]
	v_pk_mul_f32 v[166:167], v[166:167], s[84:85] op_sel_hi:[1,0]
	v_pk_fma_f32 v[16:17], v[16:17], v[144:145], v[164:165]
	v_pk_fma_f32 v[18:19], v[18:19], v[146:147], v[166:167]
	v_cvt_pk_f16_f32 v174, v16, v17
	v_cvt_pk_f16_f32 v175, v18, v19
	global_store_dwordx2 v177, v[174:175], s[80:81] offset:96
	v_add_u32_e32 v177, 0x8000, v177
	v_add_u32_e32 v178, 0x8000, v178
	global_load_dwordx2 v[184:185], v178, s[80:81]
	global_load_dwordx2 v[186:187], v178, s[80:81] offset:32
	global_load_dwordx2 v[188:189], v178, s[80:81] offset:64
	global_load_dwordx2 v[190:191], v178, s[80:81] offset:96
	s_waitcnt vmcnt(11)
	v_cvt_f32_f16_e32 v164, v238
	v_cvt_f32_f16_sdwa v165, v238 dst_sel:DWORD dst_unused:UNUSED_PAD src0_sel:WORD_1
	v_cvt_f32_f16_e32 v166, v239
	v_cvt_f32_f16_sdwa v167, v239 dst_sel:DWORD dst_unused:UNUSED_PAD src0_sel:WORD_1
	v_pk_mul_f32 v[164:165], v[164:165], s[84:85] op_sel_hi:[1,0]
	v_pk_mul_f32 v[166:167], v[166:167], s[84:85] op_sel_hi:[1,0]
	v_pk_fma_f32 v[20:21], v[20:21], v[132:133], v[164:165]
	v_pk_fma_f32 v[22:23], v[22:23], v[134:135], v[166:167]
	v_cvt_pk_f16_f32 v172, v20, v21
	v_cvt_pk_f16_f32 v173, v22, v23
	global_store_dwordx2 v177, v[172:173], s[80:81]
	s_waitcnt vmcnt(11)
	v_cvt_f32_f16_e32 v164, v240
	v_cvt_f32_f16_sdwa v165, v240 dst_sel:DWORD dst_unused:UNUSED_PAD src0_sel:WORD_1
	v_cvt_f32_f16_e32 v166, v241
	v_cvt_f32_f16_sdwa v167, v241 dst_sel:DWORD dst_unused:UNUSED_PAD src0_sel:WORD_1
	v_pk_mul_f32 v[164:165], v[164:165], s[84:85] op_sel_hi:[1,0]
	v_pk_mul_f32 v[166:167], v[166:167], s[84:85] op_sel_hi:[1,0]
	v_pk_fma_f32 v[24:25], v[24:25], v[136:137], v[164:165]
	v_pk_fma_f32 v[26:27], v[26:27], v[138:139], v[166:167]
	v_cvt_pk_f16_f32 v174, v24, v25
	v_cvt_pk_f16_f32 v175, v26, v27
	global_store_dwordx2 v177, v[174:175], s[80:81] offset:32
	s_waitcnt vmcnt(11)
	v_cvt_f32_f16_e32 v164, v242
	v_cvt_f32_f16_sdwa v165, v242 dst_sel:DWORD dst_unused:UNUSED_PAD src0_sel:WORD_1
	v_cvt_f32_f16_e32 v166, v243
	v_cvt_f32_f16_sdwa v167, v243 dst_sel:DWORD dst_unused:UNUSED_PAD src0_sel:WORD_1
	v_pk_mul_f32 v[164:165], v[164:165], s[84:85] op_sel_hi:[1,0]
	v_pk_mul_f32 v[166:167], v[166:167], s[84:85] op_sel_hi:[1,0]
	v_pk_fma_f32 v[28:29], v[28:29], v[140:141], v[164:165]
	v_pk_fma_f32 v[30:31], v[30:31], v[142:143], v[166:167]
	v_cvt_pk_f16_f32 v172, v28, v29
	v_cvt_pk_f16_f32 v173, v30, v31
	global_store_dwordx2 v177, v[172:173], s[80:81] offset:64
	s_waitcnt vmcnt(11)
	v_cvt_f32_f16_e32 v164, v244
	v_cvt_f32_f16_sdwa v165, v244 dst_sel:DWORD dst_unused:UNUSED_PAD src0_sel:WORD_1
	v_cvt_f32_f16_e32 v166, v245
	v_cvt_f32_f16_sdwa v167, v245 dst_sel:DWORD dst_unused:UNUSED_PAD src0_sel:WORD_1
	v_pk_mul_f32 v[164:165], v[164:165], s[84:85] op_sel_hi:[1,0]
	v_pk_mul_f32 v[166:167], v[166:167], s[84:85] op_sel_hi:[1,0]
	v_pk_fma_f32 v[32:33], v[32:33], v[144:145], v[164:165]
	v_pk_fma_f32 v[34:35], v[34:35], v[146:147], v[166:167]
	v_cvt_pk_f16_f32 v174, v32, v33
	v_cvt_pk_f16_f32 v175, v34, v35
	global_store_dwordx2 v177, v[174:175], s[80:81] offset:96
	v_add_u32_e32 v177, 0x8000, v177
	v_add_u32_e32 v178, 0x8000, v178
	global_load_dwordx2 v[238:239], v178, s[80:81]
	global_load_dwordx2 v[240:241], v178, s[80:81] offset:32
	global_load_dwordx2 v[242:243], v178, s[80:81] offset:64
	global_load_dwordx2 v[244:245], v178, s[80:81] offset:96
	s_waitcnt vmcnt(11)
	v_cvt_f32_f16_e32 v164, v184
	v_cvt_f32_f16_sdwa v165, v184 dst_sel:DWORD dst_unused:UNUSED_PAD src0_sel:WORD_1
	v_cvt_f32_f16_e32 v166, v185
	v_cvt_f32_f16_sdwa v167, v185 dst_sel:DWORD dst_unused:UNUSED_PAD src0_sel:WORD_1
	v_pk_mul_f32 v[164:165], v[164:165], s[84:85] op_sel_hi:[1,0]
	v_pk_mul_f32 v[166:167], v[166:167], s[84:85] op_sel_hi:[1,0]
	v_pk_fma_f32 v[36:37], v[36:37], v[132:133], v[164:165]
	v_pk_fma_f32 v[38:39], v[38:39], v[134:135], v[166:167]
	v_cvt_pk_f16_f32 v172, v36, v37
	v_cvt_pk_f16_f32 v173, v38, v39
	global_store_dwordx2 v177, v[172:173], s[80:81]
	s_waitcnt vmcnt(11)
	v_cvt_f32_f16_e32 v164, v186
	v_cvt_f32_f16_sdwa v165, v186 dst_sel:DWORD dst_unused:UNUSED_PAD src0_sel:WORD_1
	v_cvt_f32_f16_e32 v166, v187
	v_cvt_f32_f16_sdwa v167, v187 dst_sel:DWORD dst_unused:UNUSED_PAD src0_sel:WORD_1
	v_pk_mul_f32 v[164:165], v[164:165], s[84:85] op_sel_hi:[1,0]
	v_pk_mul_f32 v[166:167], v[166:167], s[84:85] op_sel_hi:[1,0]
	v_pk_fma_f32 v[40:41], v[40:41], v[136:137], v[164:165]
	v_pk_fma_f32 v[42:43], v[42:43], v[138:139], v[166:167]
	v_cvt_pk_f16_f32 v174, v40, v41
	v_cvt_pk_f16_f32 v175, v42, v43
	global_store_dwordx2 v177, v[174:175], s[80:81] offset:32
	s_waitcnt vmcnt(11)
	v_cvt_f32_f16_e32 v164, v188
	v_cvt_f32_f16_sdwa v165, v188 dst_sel:DWORD dst_unused:UNUSED_PAD src0_sel:WORD_1
	v_cvt_f32_f16_e32 v166, v189
	v_cvt_f32_f16_sdwa v167, v189 dst_sel:DWORD dst_unused:UNUSED_PAD src0_sel:WORD_1
	v_pk_mul_f32 v[164:165], v[164:165], s[84:85] op_sel_hi:[1,0]
	v_pk_mul_f32 v[166:167], v[166:167], s[84:85] op_sel_hi:[1,0]
	v_pk_fma_f32 v[44:45], v[44:45], v[140:141], v[164:165]
	v_pk_fma_f32 v[46:47], v[46:47], v[142:143], v[166:167]
	v_cvt_pk_f16_f32 v172, v44, v45
	v_cvt_pk_f16_f32 v173, v46, v47
	global_store_dwordx2 v177, v[172:173], s[80:81] offset:64
	s_waitcnt vmcnt(11)
	v_cvt_f32_f16_e32 v164, v190
	v_cvt_f32_f16_sdwa v165, v190 dst_sel:DWORD dst_unused:UNUSED_PAD src0_sel:WORD_1
	v_cvt_f32_f16_e32 v166, v191
	v_cvt_f32_f16_sdwa v167, v191 dst_sel:DWORD dst_unused:UNUSED_PAD src0_sel:WORD_1
	v_pk_mul_f32 v[164:165], v[164:165], s[84:85] op_sel_hi:[1,0]
	v_pk_mul_f32 v[166:167], v[166:167], s[84:85] op_sel_hi:[1,0]
	v_pk_fma_f32 v[48:49], v[48:49], v[144:145], v[164:165]
	v_pk_fma_f32 v[50:51], v[50:51], v[146:147], v[166:167]
	v_cvt_pk_f16_f32 v174, v48, v49
	v_cvt_pk_f16_f32 v175, v50, v51
	global_store_dwordx2 v177, v[174:175], s[80:81] offset:96
	v_add_u32_e32 v177, 0x8000, v177
	v_add_u32_e32 v178, 0x8000, v178
	global_load_dwordx2 v[184:185], v178, s[80:81]
	global_load_dwordx2 v[186:187], v178, s[80:81] offset:32
	global_load_dwordx2 v[188:189], v178, s[80:81] offset:64
	global_load_dwordx2 v[190:191], v178, s[80:81] offset:96
	s_waitcnt vmcnt(11)
	v_cvt_f32_f16_e32 v164, v238
	v_cvt_f32_f16_sdwa v165, v238 dst_sel:DWORD dst_unused:UNUSED_PAD src0_sel:WORD_1
	v_cvt_f32_f16_e32 v166, v239
	v_cvt_f32_f16_sdwa v167, v239 dst_sel:DWORD dst_unused:UNUSED_PAD src0_sel:WORD_1
	v_pk_mul_f32 v[164:165], v[164:165], s[84:85] op_sel_hi:[1,0]
	v_pk_mul_f32 v[166:167], v[166:167], s[84:85] op_sel_hi:[1,0]
	v_pk_fma_f32 v[52:53], v[52:53], v[132:133], v[164:165]
	v_pk_fma_f32 v[54:55], v[54:55], v[134:135], v[166:167]
	v_cvt_pk_f16_f32 v172, v52, v53
	v_cvt_pk_f16_f32 v173, v54, v55
	global_store_dwordx2 v177, v[172:173], s[80:81]
	s_waitcnt vmcnt(11)
	v_cvt_f32_f16_e32 v164, v240
	v_cvt_f32_f16_sdwa v165, v240 dst_sel:DWORD dst_unused:UNUSED_PAD src0_sel:WORD_1
	v_cvt_f32_f16_e32 v166, v241
	v_cvt_f32_f16_sdwa v167, v241 dst_sel:DWORD dst_unused:UNUSED_PAD src0_sel:WORD_1
	v_pk_mul_f32 v[164:165], v[164:165], s[84:85] op_sel_hi:[1,0]
	v_pk_mul_f32 v[166:167], v[166:167], s[84:85] op_sel_hi:[1,0]
	v_pk_fma_f32 v[56:57], v[56:57], v[136:137], v[164:165]
	v_pk_fma_f32 v[58:59], v[58:59], v[138:139], v[166:167]
	v_cvt_pk_f16_f32 v174, v56, v57
	v_cvt_pk_f16_f32 v175, v58, v59
	global_store_dwordx2 v177, v[174:175], s[80:81] offset:32
	s_waitcnt vmcnt(11)
	v_cvt_f32_f16_e32 v164, v242
	v_cvt_f32_f16_sdwa v165, v242 dst_sel:DWORD dst_unused:UNUSED_PAD src0_sel:WORD_1
	v_cvt_f32_f16_e32 v166, v243
	v_cvt_f32_f16_sdwa v167, v243 dst_sel:DWORD dst_unused:UNUSED_PAD src0_sel:WORD_1
	v_pk_mul_f32 v[164:165], v[164:165], s[84:85] op_sel_hi:[1,0]
	v_pk_mul_f32 v[166:167], v[166:167], s[84:85] op_sel_hi:[1,0]
	v_pk_fma_f32 v[60:61], v[60:61], v[140:141], v[164:165]
	v_pk_fma_f32 v[62:63], v[62:63], v[142:143], v[166:167]
	v_cvt_pk_f16_f32 v172, v60, v61
	v_cvt_pk_f16_f32 v173, v62, v63
	global_store_dwordx2 v177, v[172:173], s[80:81] offset:64
	s_waitcnt vmcnt(11)
	v_cvt_f32_f16_e32 v164, v244
	v_cvt_f32_f16_sdwa v165, v244 dst_sel:DWORD dst_unused:UNUSED_PAD src0_sel:WORD_1
	v_cvt_f32_f16_e32 v166, v245
	v_cvt_f32_f16_sdwa v167, v245 dst_sel:DWORD dst_unused:UNUSED_PAD src0_sel:WORD_1
	v_pk_mul_f32 v[164:165], v[164:165], s[84:85] op_sel_hi:[1,0]
	v_pk_mul_f32 v[166:167], v[166:167], s[84:85] op_sel_hi:[1,0]
	v_pk_fma_f32 v[64:65], v[64:65], v[144:145], v[164:165]
	v_pk_fma_f32 v[66:67], v[66:67], v[146:147], v[166:167]
	v_cvt_pk_f16_f32 v174, v64, v65
	v_cvt_pk_f16_f32 v175, v66, v67
	global_store_dwordx2 v177, v[174:175], s[80:81] offset:96
	v_add_u32_e32 v177, 0x8000, v177
	v_add_u32_e32 v178, 0x8000, v178
	global_load_dwordx2 v[238:239], v178, s[80:81]
	global_load_dwordx2 v[240:241], v178, s[80:81] offset:32
	global_load_dwordx2 v[242:243], v178, s[80:81] offset:64
	global_load_dwordx2 v[244:245], v178, s[80:81] offset:96
	s_waitcnt vmcnt(11)
	v_cvt_f32_f16_e32 v164, v184
	v_cvt_f32_f16_sdwa v165, v184 dst_sel:DWORD dst_unused:UNUSED_PAD src0_sel:WORD_1
	v_cvt_f32_f16_e32 v166, v185
	v_cvt_f32_f16_sdwa v167, v185 dst_sel:DWORD dst_unused:UNUSED_PAD src0_sel:WORD_1
	v_pk_mul_f32 v[164:165], v[164:165], s[84:85] op_sel_hi:[1,0]
	v_pk_mul_f32 v[166:167], v[166:167], s[84:85] op_sel_hi:[1,0]
	v_pk_fma_f32 v[68:69], v[68:69], v[132:133], v[164:165]
	v_pk_fma_f32 v[70:71], v[70:71], v[134:135], v[166:167]
	v_cvt_pk_f16_f32 v172, v68, v69
	v_cvt_pk_f16_f32 v173, v70, v71
	global_store_dwordx2 v177, v[172:173], s[80:81]
	s_waitcnt vmcnt(11)
	v_cvt_f32_f16_e32 v164, v186
	v_cvt_f32_f16_sdwa v165, v186 dst_sel:DWORD dst_unused:UNUSED_PAD src0_sel:WORD_1
	v_cvt_f32_f16_e32 v166, v187
	v_cvt_f32_f16_sdwa v167, v187 dst_sel:DWORD dst_unused:UNUSED_PAD src0_sel:WORD_1
	v_pk_mul_f32 v[164:165], v[164:165], s[84:85] op_sel_hi:[1,0]
	v_pk_mul_f32 v[166:167], v[166:167], s[84:85] op_sel_hi:[1,0]
	v_pk_fma_f32 v[72:73], v[72:73], v[136:137], v[164:165]
	v_pk_fma_f32 v[74:75], v[74:75], v[138:139], v[166:167]
	v_cvt_pk_f16_f32 v174, v72, v73
	v_cvt_pk_f16_f32 v175, v74, v75
	global_store_dwordx2 v177, v[174:175], s[80:81] offset:32
	s_waitcnt vmcnt(11)
	v_cvt_f32_f16_e32 v164, v188
	v_cvt_f32_f16_sdwa v165, v188 dst_sel:DWORD dst_unused:UNUSED_PAD src0_sel:WORD_1
	v_cvt_f32_f16_e32 v166, v189
	v_cvt_f32_f16_sdwa v167, v189 dst_sel:DWORD dst_unused:UNUSED_PAD src0_sel:WORD_1
	v_pk_mul_f32 v[164:165], v[164:165], s[84:85] op_sel_hi:[1,0]
	v_pk_mul_f32 v[166:167], v[166:167], s[84:85] op_sel_hi:[1,0]
	v_pk_fma_f32 v[76:77], v[76:77], v[140:141], v[164:165]
	v_pk_fma_f32 v[78:79], v[78:79], v[142:143], v[166:167]
	v_cvt_pk_f16_f32 v172, v76, v77
	v_cvt_pk_f16_f32 v173, v78, v79
	global_store_dwordx2 v177, v[172:173], s[80:81] offset:64
	s_waitcnt vmcnt(11)
	v_cvt_f32_f16_e32 v164, v190
	v_cvt_f32_f16_sdwa v165, v190 dst_sel:DWORD dst_unused:UNUSED_PAD src0_sel:WORD_1
	v_cvt_f32_f16_e32 v166, v191
	v_cvt_f32_f16_sdwa v167, v191 dst_sel:DWORD dst_unused:UNUSED_PAD src0_sel:WORD_1
	v_pk_mul_f32 v[164:165], v[164:165], s[84:85] op_sel_hi:[1,0]
	v_pk_mul_f32 v[166:167], v[166:167], s[84:85] op_sel_hi:[1,0]
	v_pk_fma_f32 v[80:81], v[80:81], v[144:145], v[164:165]
	v_pk_fma_f32 v[82:83], v[82:83], v[146:147], v[166:167]
	v_cvt_pk_f16_f32 v174, v80, v81
	v_cvt_pk_f16_f32 v175, v82, v83
	global_store_dwordx2 v177, v[174:175], s[80:81] offset:96
	v_add_u32_e32 v177, 0x8000, v177
	v_add_u32_e32 v178, 0x8000, v178
	global_load_dwordx2 v[184:185], v178, s[80:81]
	global_load_dwordx2 v[186:187], v178, s[80:81] offset:32
	global_load_dwordx2 v[188:189], v178, s[80:81] offset:64
	global_load_dwordx2 v[190:191], v178, s[80:81] offset:96
	s_waitcnt vmcnt(11)
	v_cvt_f32_f16_e32 v164, v238
	v_cvt_f32_f16_sdwa v165, v238 dst_sel:DWORD dst_unused:UNUSED_PAD src0_sel:WORD_1
	v_cvt_f32_f16_e32 v166, v239
	v_cvt_f32_f16_sdwa v167, v239 dst_sel:DWORD dst_unused:UNUSED_PAD src0_sel:WORD_1
	v_pk_mul_f32 v[164:165], v[164:165], s[84:85] op_sel_hi:[1,0]
	v_pk_mul_f32 v[166:167], v[166:167], s[84:85] op_sel_hi:[1,0]
	v_pk_fma_f32 v[84:85], v[84:85], v[132:133], v[164:165]
	v_pk_fma_f32 v[86:87], v[86:87], v[134:135], v[166:167]
	v_cvt_pk_f16_f32 v172, v84, v85
	v_cvt_pk_f16_f32 v173, v86, v87
	global_store_dwordx2 v177, v[172:173], s[80:81]
	s_waitcnt vmcnt(11)
	v_cvt_f32_f16_e32 v164, v240
	v_cvt_f32_f16_sdwa v165, v240 dst_sel:DWORD dst_unused:UNUSED_PAD src0_sel:WORD_1
	v_cvt_f32_f16_e32 v166, v241
	v_cvt_f32_f16_sdwa v167, v241 dst_sel:DWORD dst_unused:UNUSED_PAD src0_sel:WORD_1
	v_pk_mul_f32 v[164:165], v[164:165], s[84:85] op_sel_hi:[1,0]
	v_pk_mul_f32 v[166:167], v[166:167], s[84:85] op_sel_hi:[1,0]
	v_pk_fma_f32 v[88:89], v[88:89], v[136:137], v[164:165]
	v_pk_fma_f32 v[90:91], v[90:91], v[138:139], v[166:167]
	v_cvt_pk_f16_f32 v174, v88, v89
	v_cvt_pk_f16_f32 v175, v90, v91
	global_store_dwordx2 v177, v[174:175], s[80:81] offset:32
	s_waitcnt vmcnt(11)
	v_cvt_f32_f16_e32 v164, v242
	v_cvt_f32_f16_sdwa v165, v242 dst_sel:DWORD dst_unused:UNUSED_PAD src0_sel:WORD_1
	v_cvt_f32_f16_e32 v166, v243
	v_cvt_f32_f16_sdwa v167, v243 dst_sel:DWORD dst_unused:UNUSED_PAD src0_sel:WORD_1
	v_pk_mul_f32 v[164:165], v[164:165], s[84:85] op_sel_hi:[1,0]
	v_pk_mul_f32 v[166:167], v[166:167], s[84:85] op_sel_hi:[1,0]
	v_pk_fma_f32 v[92:93], v[92:93], v[140:141], v[164:165]
	v_pk_fma_f32 v[94:95], v[94:95], v[142:143], v[166:167]
	v_cvt_pk_f16_f32 v172, v92, v93
	v_cvt_pk_f16_f32 v173, v94, v95
	global_store_dwordx2 v177, v[172:173], s[80:81] offset:64
	s_waitcnt vmcnt(11)
	v_cvt_f32_f16_e32 v164, v244
	v_cvt_f32_f16_sdwa v165, v244 dst_sel:DWORD dst_unused:UNUSED_PAD src0_sel:WORD_1
	v_cvt_f32_f16_e32 v166, v245
	v_cvt_f32_f16_sdwa v167, v245 dst_sel:DWORD dst_unused:UNUSED_PAD src0_sel:WORD_1
	v_pk_mul_f32 v[164:165], v[164:165], s[84:85] op_sel_hi:[1,0]
	v_pk_mul_f32 v[166:167], v[166:167], s[84:85] op_sel_hi:[1,0]
	v_pk_fma_f32 v[96:97], v[96:97], v[144:145], v[164:165]
	v_pk_fma_f32 v[98:99], v[98:99], v[146:147], v[166:167]
	v_cvt_pk_f16_f32 v174, v96, v97
	v_cvt_pk_f16_f32 v175, v98, v99
	global_store_dwordx2 v177, v[174:175], s[80:81] offset:96
	v_add_u32_e32 v177, 0x8000, v177
	v_add_u32_e32 v178, 0x8000, v178
	global_load_dwordx2 v[238:239], v178, s[80:81]
	global_load_dwordx2 v[240:241], v178, s[80:81] offset:32
	global_load_dwordx2 v[242:243], v178, s[80:81] offset:64
	global_load_dwordx2 v[244:245], v178, s[80:81] offset:96
	s_waitcnt vmcnt(11)
	v_cvt_f32_f16_e32 v164, v184
	v_cvt_f32_f16_sdwa v165, v184 dst_sel:DWORD dst_unused:UNUSED_PAD src0_sel:WORD_1
	v_cvt_f32_f16_e32 v166, v185
	v_cvt_f32_f16_sdwa v167, v185 dst_sel:DWORD dst_unused:UNUSED_PAD src0_sel:WORD_1
	v_pk_mul_f32 v[164:165], v[164:165], s[84:85] op_sel_hi:[1,0]
	v_pk_mul_f32 v[166:167], v[166:167], s[84:85] op_sel_hi:[1,0]
	v_pk_fma_f32 v[100:101], v[100:101], v[132:133], v[164:165]
	v_pk_fma_f32 v[102:103], v[102:103], v[134:135], v[166:167]
	v_cvt_pk_f16_f32 v172, v100, v101
	v_cvt_pk_f16_f32 v173, v102, v103
	global_store_dwordx2 v177, v[172:173], s[80:81]
	s_waitcnt vmcnt(11)
	v_cvt_f32_f16_e32 v164, v186
	v_cvt_f32_f16_sdwa v165, v186 dst_sel:DWORD dst_unused:UNUSED_PAD src0_sel:WORD_1
	v_cvt_f32_f16_e32 v166, v187
	v_cvt_f32_f16_sdwa v167, v187 dst_sel:DWORD dst_unused:UNUSED_PAD src0_sel:WORD_1
	v_pk_mul_f32 v[164:165], v[164:165], s[84:85] op_sel_hi:[1,0]
	v_pk_mul_f32 v[166:167], v[166:167], s[84:85] op_sel_hi:[1,0]
	v_pk_fma_f32 v[104:105], v[104:105], v[136:137], v[164:165]
	v_pk_fma_f32 v[106:107], v[106:107], v[138:139], v[166:167]
	v_cvt_pk_f16_f32 v174, v104, v105
	v_cvt_pk_f16_f32 v175, v106, v107
	global_store_dwordx2 v177, v[174:175], s[80:81] offset:32
	s_waitcnt vmcnt(11)
	v_cvt_f32_f16_e32 v164, v188
	v_cvt_f32_f16_sdwa v165, v188 dst_sel:DWORD dst_unused:UNUSED_PAD src0_sel:WORD_1
	v_cvt_f32_f16_e32 v166, v189
	v_cvt_f32_f16_sdwa v167, v189 dst_sel:DWORD dst_unused:UNUSED_PAD src0_sel:WORD_1
	v_pk_mul_f32 v[164:165], v[164:165], s[84:85] op_sel_hi:[1,0]
	v_pk_mul_f32 v[166:167], v[166:167], s[84:85] op_sel_hi:[1,0]
	v_pk_fma_f32 v[108:109], v[108:109], v[140:141], v[164:165]
	v_pk_fma_f32 v[110:111], v[110:111], v[142:143], v[166:167]
	v_cvt_pk_f16_f32 v172, v108, v109
	v_cvt_pk_f16_f32 v173, v110, v111
	global_store_dwordx2 v177, v[172:173], s[80:81] offset:64
	s_waitcnt vmcnt(11)
	v_cvt_f32_f16_e32 v164, v190
	v_cvt_f32_f16_sdwa v165, v190 dst_sel:DWORD dst_unused:UNUSED_PAD src0_sel:WORD_1
	v_cvt_f32_f16_e32 v166, v191
	v_cvt_f32_f16_sdwa v167, v191 dst_sel:DWORD dst_unused:UNUSED_PAD src0_sel:WORD_1
	v_pk_mul_f32 v[164:165], v[164:165], s[84:85] op_sel_hi:[1,0]
	v_pk_mul_f32 v[166:167], v[166:167], s[84:85] op_sel_hi:[1,0]
	v_pk_fma_f32 v[112:113], v[112:113], v[144:145], v[164:165]
	v_pk_fma_f32 v[114:115], v[114:115], v[146:147], v[166:167]
	v_cvt_pk_f16_f32 v174, v112, v113
	v_cvt_pk_f16_f32 v175, v114, v115
	global_store_dwordx2 v177, v[174:175], s[80:81] offset:96
	v_add_u32_e32 v177, 0x8000, v177
	s_waitcnt vmcnt(7)
	v_cvt_f32_f16_e32 v164, v238
	v_cvt_f32_f16_sdwa v165, v238 dst_sel:DWORD dst_unused:UNUSED_PAD src0_sel:WORD_1
	v_cvt_f32_f16_e32 v166, v239
	v_cvt_f32_f16_sdwa v167, v239 dst_sel:DWORD dst_unused:UNUSED_PAD src0_sel:WORD_1
	v_pk_mul_f32 v[164:165], v[164:165], s[84:85] op_sel_hi:[1,0]
	v_pk_mul_f32 v[166:167], v[166:167], s[84:85] op_sel_hi:[1,0]
	v_pk_fma_f32 v[116:117], v[116:117], v[132:133], v[164:165]
	v_pk_fma_f32 v[118:119], v[118:119], v[134:135], v[166:167]
	v_cvt_pk_f16_f32 v172, v116, v117
	v_cvt_pk_f16_f32 v173, v118, v119
	global_store_dwordx2 v177, v[172:173], s[80:81]
	s_waitcnt vmcnt(7)
	v_cvt_f32_f16_e32 v164, v240
	v_cvt_f32_f16_sdwa v165, v240 dst_sel:DWORD dst_unused:UNUSED_PAD src0_sel:WORD_1
	v_cvt_f32_f16_e32 v166, v241
	v_cvt_f32_f16_sdwa v167, v241 dst_sel:DWORD dst_unused:UNUSED_PAD src0_sel:WORD_1
	v_pk_mul_f32 v[164:165], v[164:165], s[84:85] op_sel_hi:[1,0]
	v_pk_mul_f32 v[166:167], v[166:167], s[84:85] op_sel_hi:[1,0]
	v_pk_fma_f32 v[120:121], v[120:121], v[136:137], v[164:165]
	v_pk_fma_f32 v[122:123], v[122:123], v[138:139], v[166:167]
	v_cvt_pk_f16_f32 v174, v120, v121
	v_cvt_pk_f16_f32 v175, v122, v123
	global_store_dwordx2 v177, v[174:175], s[80:81] offset:32
	s_waitcnt vmcnt(7)
	v_cvt_f32_f16_e32 v164, v242
	v_cvt_f32_f16_sdwa v165, v242 dst_sel:DWORD dst_unused:UNUSED_PAD src0_sel:WORD_1
	v_cvt_f32_f16_e32 v166, v243
	v_cvt_f32_f16_sdwa v167, v243 dst_sel:DWORD dst_unused:UNUSED_PAD src0_sel:WORD_1
	v_pk_mul_f32 v[164:165], v[164:165], s[84:85] op_sel_hi:[1,0]
	v_pk_mul_f32 v[166:167], v[166:167], s[84:85] op_sel_hi:[1,0]
	v_pk_fma_f32 v[124:125], v[124:125], v[140:141], v[164:165]
	v_pk_fma_f32 v[126:127], v[126:127], v[142:143], v[166:167]
	v_cvt_pk_f16_f32 v172, v124, v125
	v_cvt_pk_f16_f32 v173, v126, v127
	global_store_dwordx2 v177, v[172:173], s[80:81] offset:64
	s_waitcnt vmcnt(7)
	v_cvt_f32_f16_e32 v164, v244
	v_cvt_f32_f16_sdwa v165, v244 dst_sel:DWORD dst_unused:UNUSED_PAD src0_sel:WORD_1
	v_cvt_f32_f16_e32 v166, v245
	v_cvt_f32_f16_sdwa v167, v245 dst_sel:DWORD dst_unused:UNUSED_PAD src0_sel:WORD_1
	v_pk_mul_f32 v[164:165], v[164:165], s[84:85] op_sel_hi:[1,0]
	v_pk_mul_f32 v[166:167], v[166:167], s[84:85] op_sel_hi:[1,0]
	v_pk_fma_f32 v[128:129], v[128:129], v[144:145], v[164:165]
	v_pk_fma_f32 v[130:131], v[130:131], v[146:147], v[166:167]
	v_cvt_pk_f16_f32 v174, v128, v129
	v_cvt_pk_f16_f32 v175, v130, v131
	global_store_dwordx2 v177, v[174:175], s[80:81] offset:96
	s_nop 1
	s_branch .LBB0_67

.LBB0_695:
	s_andn2_b64 vcc, exec, s[28:29]
	s_cbranch_vccnz .LBB0_716
	s_load_dwordx2 s[44:45], s[22:23], 0x110
	s_load_dwordx2 s[42:43], s[22:23], 0x80
	v_readlane_b32 s24, v236, 15
	v_readlane_b32 s25, v236, 16
	s_mov_b64 s[28:29], -1
	s_waitcnt lgkmcnt(0)
	s_add_u32 s48, s44, 0x1500000
	s_addc_u32 s49, s45, 0
	s_add_u32 s46, s44, 0x3208000
	s_addc_u32 s47, s45, 0
	s_and_b64 vcc, exec, s[24:25]
	s_cbranch_vccz .LBB0_760
	v_readlane_b32 s24, v236, 1
	v_readlane_b32 s25, v236, 2
	s_andn2_b64 vcc, exec, s[24:25]
	s_cbranch_vccnz .LBB0_759
	s_add_u32 s28, s44, 0xaa08000
	s_addc_u32 s29, s45, 0
	v_readlane_b32 s24, v236, 0
	s_and_b32 s65, s24, 7
	s_lshr_b32 s35, s24, 6
	s_lshl_b32 s35, s35, 3
	s_or_b32 s65, s65, s35
	s_and_b32 s35, s24, 0x38
	s_lshr_b32 s53, s65, 2
	s_lshl_b32 s53, s53, 6
	s_and_b32 s65, s65, 3
	s_lshl_b32 s65, s65, 1
	s_add_u32 s24, s35, s53
	s_add_u32 s24, s24, s65
	s_branch .LBB0_700

.LBB0_704:
	s_waitcnt lgkmcnt(0)
	s_lshl_b64 s[50:51], s[30:31], 13
	s_add_u32 s50, s50, s36
	s_addc_u32 s51, s51, s37
	s_lshl_b32 s65, s52, 3
	s_sub_i32 s65, s24, s65
	s_lshl_b32 s30, s65, 7
	s_lshl_b32 s65, s30, 13
	s_add_u32 s54, s48, s65
	s_addc_u32 s55, s49, 0
	v_readfirstlane_b32 s65, v200
	s_lshr_b32 s65, s65, 6
	s_lshl_b32 s25, s65, 11
	s_add_u32 s25, s25, 16
	s_lshl_b32 s65, s65, 18
	s_add_u32 s50, s50, s65
	s_addc_u32 s51, s51, 0
	s_add_u32 s54, s54, s65
	s_addc_u32 s55, s55, 0
	v_bfe_u32 v173, v200, 4, 2
	v_sub_u32_e32 v173, 0, v173
	v_and_b32_e32 v173, 3, v173
	v_and_b32_e32 v172, 3, v200
	v_xor_b32_e32 v172, v172, v173
	v_bfe_u32 v173, v200, 2, 4
	v_lshlrev_b32_e32 v173, 13, v173
	v_lshl_or_b32 v170, v172, 4, v173
	v_add_u32_e32 v171, 0x20000, v170
	v_bfe_u32 v172, v200, 2, 2
	v_sub_u32_e32 v172, 0, v172
	v_and_b32_e32 v172, 3, v172
	v_bfe_u32 v173, v200, 4, 2
	v_xor_b32_e32 v172, v172, v173
	v_and_b32_e32 v173, 15, v200
	v_bfe_u32 v174, v200, 8, 1
	v_lshl_or_b32 v174, v174, 7, v173
	v_lshlrev_b32_e32 v174, 6, v174
	v_lshl_or_b32 v164, v172, 4, v174
	v_bfe_u32 v174, v200, 6, 2
	v_lshl_or_b32 v174, v174, 6, v173
	v_lshlrev_b32_e32 v174, 6, v174
	v_lshl_or_b32 v165, v172, 4, v174
	v_add_u32_e32 v165, 0x4000, v165
	v_bfe_u32 v172, v200, 6, 2
	v_bfe_u32 v173, v200, 4, 2
	v_lshlrev_b32_e32 v172, 6, v172
	v_lshl_or_b32 v172, v173, 2, v172
	v_add_u32_e32 v172, s30, v172
	v_lshlrev_b32_e32 v172, 2, v172
	global_load_dwordx4 v[132:135], v172, s[42:43]
	global_load_dwordx4 v[136:139], v172, s[42:43] offset:64
	global_load_dwordx4 v[140:143], v172, s[42:43] offset:128
	global_load_dwordx4 v[144:147], v172, s[42:43] offset:192
	s_mov_b32 s35, s25
	s_mov_b32 m0, s35
	s_nop 0
	global_load_lds_dwordx4 v170, s[50:51]
	s_add_u32 m0, s35, 0x400
	s_nop 0
	global_load_lds_dwordx4 v171, s[50:51]
	s_add_u32 m0, s35, 0x4000
	s_nop 0
	global_load_lds_dwordx4 v170, s[54:55]
	s_add_u32 m0, s35, 0x4400
	s_nop 0
	global_load_lds_dwordx4 v171, s[54:55]
	s_add_u32 s50, s50, 64
	s_addc_u32 s51, s51, 0
	s_add_u32 s54, s54, 64
	s_addc_u32 s55, s55, 0
	s_add_u32 s35, s25, 0x8000
	s_mov_b32 m0, s35
	s_nop 0
	global_load_lds_dwordx4 v170, s[50:51]
	s_add_u32 m0, s35, 0x400
	s_nop 0
	global_load_lds_dwordx4 v171, s[50:51]
	s_add_u32 m0, s35, 0x4000
	s_nop 0
	global_load_lds_dwordx4 v170, s[54:55]
	s_add_u32 m0, s35, 0x4400
	s_nop 0
	global_load_lds_dwordx4 v171, s[54:55]
	s_add_u32 s50, s50, 64
	s_addc_u32 s51, s51, 0
	s_add_u32 s54, s54, 64
	s_addc_u32 s55, s55, 0
	s_add_u32 s35, s25, 0x10000
	s_mov_b32 m0, s35
	s_nop 0
	global_load_lds_dwordx4 v170, s[50:51]
	s_add_u32 m0, s35, 0x400
	s_nop 0
	global_load_lds_dwordx4 v171, s[50:51]
	s_add_u32 m0, s35, 0x4000
	s_nop 0
	global_load_lds_dwordx4 v170, s[54:55]
	s_add_u32 m0, s35, 0x4400
	s_nop 0
	global_load_lds_dwordx4 v171, s[54:55]
	s_add_u32 s50, s50, 64
	s_addc_u32 s51, s51, 0
	s_add_u32 s54, s54, 64
	s_addc_u32 s55, s55, 0
	s_add_u32 s35, s25, 0x18000
	s_mov_b32 m0, s35
	s_nop 0
	global_load_lds_dwordx4 v170, s[50:51]
	s_add_u32 m0, s35, 0x400
	s_nop 0
	global_load_lds_dwordx4 v171, s[50:51]
	s_add_u32 m0, s35, 0x4000
	s_nop 0
	global_load_lds_dwordx4 v170, s[54:55]
	s_add_u32 m0, s35, 0x4400
	s_nop 0
	global_load_lds_dwordx4 v171, s[54:55]
	s_add_u32 s50, s50, 64
	s_addc_u32 s51, s51, 0
	s_add_u32 s54, s54, 64
	s_addc_u32 s55, s55, 0
	s_waitcnt vmcnt(12)
	s_barrier
	v_mov_b32_e32 v4, v132
	v_mov_b32_e32 v5, v133
	v_mov_b32_e32 v6, v134
	v_mov_b32_e32 v7, v135
	v_mov_b32_e32 v8, v136
	v_mov_b32_e32 v9, v137
	v_mov_b32_e32 v10, v138
	v_mov_b32_e32 v11, v139
	v_mov_b32_e32 v12, v140
	v_mov_b32_e32 v13, v141
	v_mov_b32_e32 v14, v142
	v_mov_b32_e32 v15, v143
	v_mov_b32_e32 v16, v144
	v_mov_b32_e32 v17, v145
	v_mov_b32_e32 v18, v146
	v_mov_b32_e32 v19, v147
	v_mov_b32_e32 v20, v132
	v_mov_b32_e32 v21, v133
	v_mov_b32_e32 v22, v134
	v_mov_b32_e32 v23, v135
	v_mov_b32_e32 v24, v136
	v_mov_b32_e32 v25, v137
	v_mov_b32_e32 v26, v138
	v_mov_b32_e32 v27, v139
	v_mov_b32_e32 v28, v140
	v_mov_b32_e32 v29, v141
	v_mov_b32_e32 v30, v142
	v_mov_b32_e32 v31, v143
	v_mov_b32_e32 v32, v144
	v_mov_b32_e32 v33, v145
	v_mov_b32_e32 v34, v146
	v_mov_b32_e32 v35, v147
	v_mov_b32_e32 v36, v132
	v_mov_b32_e32 v37, v133
	v_mov_b32_e32 v38, v134
	v_mov_b32_e32 v39, v135
	v_mov_b32_e32 v40, v136
	v_mov_b32_e32 v41, v137
	v_mov_b32_e32 v42, v138
	v_mov_b32_e32 v43, v139
	v_mov_b32_e32 v44, v140
	v_mov_b32_e32 v45, v141
	v_mov_b32_e32 v46, v142
	v_mov_b32_e32 v47, v143
	v_mov_b32_e32 v48, v144
	v_mov_b32_e32 v49, v145
	v_mov_b32_e32 v50, v146
	v_mov_b32_e32 v51, v147
	v_mov_b32_e32 v52, v132
	v_mov_b32_e32 v53, v133
	v_mov_b32_e32 v54, v134
	v_mov_b32_e32 v55, v135
	v_mov_b32_e32 v56, v136
	v_mov_b32_e32 v57, v137
	v_mov_b32_e32 v58, v138
	v_mov_b32_e32 v59, v139
	v_mov_b32_e32 v60, v140
	v_mov_b32_e32 v61, v141
	v_mov_b32_e32 v62, v142
	v_mov_b32_e32 v63, v143
	v_mov_b32_e32 v64, v144
	v_mov_b32_e32 v65, v145
	v_mov_b32_e32 v66, v146
	v_mov_b32_e32 v67, v147
	v_mov_b32_e32 v68, v132
	v_mov_b32_e32 v69, v133
	v_mov_b32_e32 v70, v134
	v_mov_b32_e32 v71, v135
	v_mov_b32_e32 v72, v136
	v_mov_b32_e32 v73, v137
	v_mov_b32_e32 v74, v138
	v_mov_b32_e32 v75, v139
	v_mov_b32_e32 v76, v140
	v_mov_b32_e32 v77, v141
	v_mov_b32_e32 v78, v142
	v_mov_b32_e32 v79, v143
	v_mov_b32_e32 v80, v144
	v_mov_b32_e32 v81, v145
	v_mov_b32_e32 v82, v146
	v_mov_b32_e32 v83, v147
	v_mov_b32_e32 v84, v132
	v_mov_b32_e32 v85, v133
	v_mov_b32_e32 v86, v134
	v_mov_b32_e32 v87, v135
	v_mov_b32_e32 v88, v136
	v_mov_b32_e32 v89, v137
	v_mov_b32_e32 v90, v138
	v_mov_b32_e32 v91, v139
	v_mov_b32_e32 v92, v140
	v_mov_b32_e32 v93, v141
	v_mov_b32_e32 v94, v142
	v_mov_b32_e32 v95, v143
	v_mov_b32_e32 v96, v144
	v_mov_b32_e32 v97, v145
	v_mov_b32_e32 v98, v146
	v_mov_b32_e32 v99, v147
	v_mov_b32_e32 v100, v132
	v_mov_b32_e32 v101, v133
	v_mov_b32_e32 v102, v134
	v_mov_b32_e32 v103, v135
	v_mov_b32_e32 v104, v136
	v_mov_b32_e32 v105, v137
	v_mov_b32_e32 v106, v138
	v_mov_b32_e32 v107, v139
	v_mov_b32_e32 v108, v140
	v_mov_b32_e32 v109, v141
	v_mov_b32_e32 v110, v142
	v_mov_b32_e32 v111, v143
	v_mov_b32_e32 v112, v144
	v_mov_b32_e32 v113, v145
	v_mov_b32_e32 v114, v146
	v_mov_b32_e32 v115, v147
	v_mov_b32_e32 v116, v132
	v_mov_b32_e32 v117, v133
	v_mov_b32_e32 v118, v134
	v_mov_b32_e32 v119, v135
	v_mov_b32_e32 v120, v136
	v_mov_b32_e32 v121, v137
	v_mov_b32_e32 v122, v138
	v_mov_b32_e32 v123, v139
	v_mov_b32_e32 v124, v140
	v_mov_b32_e32 v125, v141
	v_mov_b32_e32 v126, v142
	v_mov_b32_e32 v127, v143
	v_mov_b32_e32 v128, v144
	v_mov_b32_e32 v129, v145
	v_mov_b32_e32 v130, v146
	v_mov_b32_e32 v131, v147
	s_mov_b32 s32, 0
	s_mov_b32 s53, 0
	s_nop 1
	v_add_u32_e32 v168, s32, v165
	v_add_u32_e32 v169, s32, v164
	ds_read_b128 v[132:135], v168 offset:16
	ds_read_b128 v[136:139], v168 offset:1040
	ds_read_b128 v[140:143], v168 offset:2064
	ds_read_b128 v[144:147], v168 offset:3088
	ds_read_b128 v[184:187], v169 offset:16
	ds_read_b128 v[188:191], v169 offset:1040
	ds_read_b128 v[192:195], v169 offset:2064
	ds_read_b128 v[196:199], v169 offset:3088
	s_waitcnt lgkmcnt(0)
.Lt_mlp2a:
	v_add_u32_e32 v169, s32, v164
	v_mfma_f32_16x16x32_f16 v[4:7], v[132:135], v[184:187], v[4:7]
	ds_read_b128 v[238:241], v169 offset:4112
	v_mfma_f32_16x16x32_f16 v[8:11], v[136:139], v[184:187], v[8:11]
	ds_read_b128 v[242:245], v169 offset:5136
	v_mfma_f32_16x16x32_f16 v[12:15], v[140:143], v[184:187], v[12:15]
	ds_read_b128 v[246:249], v169 offset:6160
	v_mfma_f32_16x16x32_f16 v[16:19], v[144:147], v[184:187], v[16:19]
	ds_read_b128 v[250:253], v169 offset:7184
	v_mfma_f32_16x16x32_f16 v[20:23], v[132:135], v[188:191], v[20:23]
	v_mfma_f32_16x16x32_f16 v[24:27], v[136:139], v[188:191], v[24:27]
	v_mfma_f32_16x16x32_f16 v[28:31], v[140:143], v[188:191], v[28:31]
	v_mfma_f32_16x16x32_f16 v[32:35], v[144:147], v[188:191], v[32:35]
	v_mfma_f32_16x16x32_f16 v[36:39], v[132:135], v[192:195], v[36:39]
	v_mfma_f32_16x16x32_f16 v[40:43], v[136:139], v[192:195], v[40:43]
	v_mfma_f32_16x16x32_f16 v[44:47], v[140:143], v[192:195], v[44:47]
	v_mfma_f32_16x16x32_f16 v[48:51], v[144:147], v[192:195], v[48:51]
	v_mfma_f32_16x16x32_f16 v[52:55], v[132:135], v[196:199], v[52:55]
	v_mfma_f32_16x16x32_f16 v[56:59], v[136:139], v[196:199], v[56:59]
	v_mfma_f32_16x16x32_f16 v[60:63], v[140:143], v[196:199], v[60:63]
	v_mfma_f32_16x16x32_f16 v[64:67], v[144:147], v[196:199], v[64:67]
	s_waitcnt vmcnt(8) lgkmcnt(0)
	s_barrier
	s_add_i32 s35, s32, 0x8000
	s_cmp_lg_u32 s32, 0x18000
	s_cselect_b32 s35, s35, 0
	v_add_u32_e32 v168, s35, v165
	v_add_u32_e32 v169, s35, v164
	s_add_u32 vcc_lo, s25, s32
	v_mfma_f32_16x16x32_f16 v[68:71], v[132:135], v[238:241], v[68:71]
	ds_read_b128 v[148:151], v168 offset:16
	ds_read_b128 v[184:187], v169 offset:16
	v_mfma_f32_16x16x32_f16 v[72:75], v[136:139], v[238:241], v[72:75]
	ds_read_b128 v[152:155], v168 offset:1040
	ds_read_b128 v[188:191], v169 offset:1040
	v_mfma_f32_16x16x32_f16 v[76:79], v[140:143], v[238:241], v[76:79]
	ds_read_b128 v[156:159], v168 offset:2064
	ds_read_b128 v[192:195], v169 offset:2064
	v_mfma_f32_16x16x32_f16 v[80:83], v[144:147], v[238:241], v[80:83]
	ds_read_b128 v[160:163], v168 offset:3088
	ds_read_b128 v[196:199], v169 offset:3088
	v_mfma_f32_16x16x32_f16 v[84:87], v[132:135], v[242:245], v[84:87]
	v_mfma_f32_16x16x32_f16 v[88:91], v[136:139], v[242:245], v[88:91]
	v_mfma_f32_16x16x32_f16 v[92:95], v[140:143], v[242:245], v[92:95]
	v_mfma_f32_16x16x32_f16 v[96:99], v[144:147], v[242:245], v[96:99]
	v_mfma_f32_16x16x32_f16 v[100:103], v[132:135], v[246:249], v[100:103]
	s_mov_b32 m0, vcc_lo
	s_nop 0
	global_load_lds_dwordx4 v170, s[50:51]
	v_mfma_f32_16x16x32_f16 v[104:107], v[136:139], v[246:249], v[104:107]
	s_add_u32 m0, vcc_lo, 0x400
	s_nop 0
	global_load_lds_dwordx4 v171, s[50:51]
	v_mfma_f32_16x16x32_f16 v[108:111], v[140:143], v[246:249], v[108:111]
	s_add_u32 m0, vcc_lo, 0x4000
	s_nop 0
	global_load_lds_dwordx4 v170, s[54:55]
	v_mfma_f32_16x16x32_f16 v[112:115], v[144:147], v[246:249], v[112:115]
	s_add_u32 m0, vcc_lo, 0x4400
	s_nop 0
	global_load_lds_dwordx4 v171, s[54:55]
	v_mfma_f32_16x16x32_f16 v[116:119], v[132:135], v[250:253], v[116:119]
	v_mfma_f32_16x16x32_f16 v[120:123], v[136:139], v[250:253], v[120:123]
	v_mfma_f32_16x16x32_f16 v[124:127], v[140:143], v[250:253], v[124:127]
	v_mfma_f32_16x16x32_f16 v[128:131], v[144:147], v[250:253], v[128:131]
	s_waitcnt lgkmcnt(0)
	s_mov_b32 s32, s35
	s_add_u32 s50, s50, 64
	s_addc_u32 s51, s51, 0
	s_add_u32 s54, s54, 64
	s_addc_u32 s55, s55, 0
	v_add_u32_e32 v169, s32, v164
	v_mfma_f32_16x16x32_f16 v[4:7], v[148:151], v[184:187], v[4:7]
	ds_read_b128 v[238:241], v169 offset:4112
	v_mfma_f32_16x16x32_f16 v[8:11], v[152:155], v[184:187], v[8:11]
	ds_read_b128 v[242:245], v169 offset:5136
	v_mfma_f32_16x16x32_f16 v[12:15], v[156:159], v[184:187], v[12:15]
	ds_read_b128 v[246:249], v169 offset:6160
	v_mfma_f32_16x16x32_f16 v[16:19], v[160:163], v[184:187], v[16:19]
	ds_read_b128 v[250:253], v169 offset:7184
	v_mfma_f32_16x16x32_f16 v[20:23], v[148:151], v[188:191], v[20:23]
	v_mfma_f32_16x16x32_f16 v[24:27], v[152:155], v[188:191], v[24:27]
	v_mfma_f32_16x16x32_f16 v[28:31], v[156:159], v[188:191], v[28:31]
	v_mfma_f32_16x16x32_f16 v[32:35], v[160:163], v[188:191], v[32:35]
	v_mfma_f32_16x16x32_f16 v[36:39], v[148:151], v[192:195], v[36:39]
	v_mfma_f32_16x16x32_f16 v[40:43], v[152:155], v[192:195], v[40:43]
	v_mfma_f32_16x16x32_f16 v[44:47], v[156:159], v[192:195], v[44:47]
	v_mfma_f32_16x16x32_f16 v[48:51], v[160:163], v[192:195], v[48:51]
	v_mfma_f32_16x16x32_f16 v[52:55], v[148:151], v[196:199], v[52:55]
	v_mfma_f32_16x16x32_f16 v[56:59], v[152:155], v[196:199], v[56:59]
	v_mfma_f32_16x16x32_f16 v[60:63], v[156:159], v[196:199], v[60:63]
	v_mfma_f32_16x16x32_f16 v[64:67], v[160:163], v[196:199], v[64:67]
	s_waitcnt vmcnt(8) lgkmcnt(0)
	s_barrier
	s_add_i32 s35, s32, 0x8000
	s_cmp_lg_u32 s32, 0x18000
	s_cselect_b32 s35, s35, 0
	v_add_u32_e32 v168, s35, v165
	v_add_u32_e32 v169, s35, v164
	s_add_u32 vcc_lo, s25, s32
	v_mfma_f32_16x16x32_f16 v[68:71], v[148:151], v[238:241], v[68:71]
	ds_read_b128 v[132:135], v168 offset:16
	ds_read_b128 v[184:187], v169 offset:16
	v_mfma_f32_16x16x32_f16 v[72:75], v[152:155], v[238:241], v[72:75]
	ds_read_b128 v[136:139], v168 offset:1040
	ds_read_b128 v[188:191], v169 offset:1040
	v_mfma_f32_16x16x32_f16 v[76:79], v[156:159], v[238:241], v[76:79]
	ds_read_b128 v[140:143], v168 offset:2064
	ds_read_b128 v[192:195], v169 offset:2064
	v_mfma_f32_16x16x32_f16 v[80:83], v[160:163], v[238:241], v[80:83]
	ds_read_b128 v[144:147], v168 offset:3088
	ds_read_b128 v[196:199], v169 offset:3088
	v_mfma_f32_16x16x32_f16 v[84:87], v[148:151], v[242:245], v[84:87]
	v_mfma_f32_16x16x32_f16 v[88:91], v[152:155], v[242:245], v[88:91]
	v_mfma_f32_16x16x32_f16 v[92:95], v[156:159], v[242:245], v[92:95]
	v_mfma_f32_16x16x32_f16 v[96:99], v[160:163], v[242:245], v[96:99]
	v_mfma_f32_16x16x32_f16 v[100:103], v[148:151], v[246:249], v[100:103]
	s_mov_b32 m0, vcc_lo
	s_nop 0
	global_load_lds_dwordx4 v170, s[50:51]
	v_mfma_f32_16x16x32_f16 v[104:107], v[152:155], v[246:249], v[104:107]
	s_add_u32 m0, vcc_lo, 0x400
	s_nop 0
	global_load_lds_dwordx4 v171, s[50:51]
	v_mfma_f32_16x16x32_f16 v[108:111], v[156:159], v[246:249], v[108:111]
	s_add_u32 m0, vcc_lo, 0x4000
	s_nop 0
	global_load_lds_dwordx4 v170, s[54:55]
	v_mfma_f32_16x16x32_f16 v[112:115], v[160:163], v[246:249], v[112:115]
	s_add_u32 m0, vcc_lo, 0x4400
	s_nop 0
	global_load_lds_dwordx4 v171, s[54:55]
	v_mfma_f32_16x16x32_f16 v[116:119], v[148:151], v[250:253], v[116:119]
	v_mfma_f32_16x16x32_f16 v[120:123], v[152:155], v[250:253], v[120:123]
	v_mfma_f32_16x16x32_f16 v[124:127], v[156:159], v[250:253], v[124:127]
	v_mfma_f32_16x16x32_f16 v[128:131], v[160:163], v[250:253], v[128:131]
	s_waitcnt lgkmcnt(0)
	s_mov_b32 s32, s35
	s_add_u32 s50, s50, 64
	s_addc_u32 s51, s51, 0
	s_add_u32 s54, s54, 64
	s_addc_u32 s55, s55, 0
	s_add_i32 s53, s53, 2
	s_cmp_lt_u32 s53, 124
	s_cbranch_scc1 .Lt_mlp2a
	v_add_u32_e32 v169, s32, v164
	v_mfma_f32_16x16x32_f16 v[4:7], v[132:135], v[184:187], v[4:7]
	ds_read_b128 v[238:241], v169 offset:4112
	v_mfma_f32_16x16x32_f16 v[8:11], v[136:139], v[184:187], v[8:11]
	ds_read_b128 v[242:245], v169 offset:5136
	v_mfma_f32_16x16x32_f16 v[12:15], v[140:143], v[184:187], v[12:15]
	ds_read_b128 v[246:249], v169 offset:6160
	v_mfma_f32_16x16x32_f16 v[16:19], v[144:147], v[184:187], v[16:19]
	ds_read_b128 v[250:253], v169 offset:7184
	v_mfma_f32_16x16x32_f16 v[20:23], v[132:135], v[188:191], v[20:23]
	v_mfma_f32_16x16x32_f16 v[24:27], v[136:139], v[188:191], v[24:27]
	v_mfma_f32_16x16x32_f16 v[28:31], v[140:143], v[188:191], v[28:31]
	v_mfma_f32_16x16x32_f16 v[32:35], v[144:147], v[188:191], v[32:35]
	v_mfma_f32_16x16x32_f16 v[36:39], v[132:135], v[192:195], v[36:39]
	v_mfma_f32_16x16x32_f16 v[40:43], v[136:139], v[192:195], v[40:43]
	v_mfma_f32_16x16x32_f16 v[44:47], v[140:143], v[192:195], v[44:47]
	v_mfma_f32_16x16x32_f16 v[48:51], v[144:147], v[192:195], v[48:51]
	v_mfma_f32_16x16x32_f16 v[52:55], v[132:135], v[196:199], v[52:55]
	v_mfma_f32_16x16x32_f16 v[56:59], v[136:139], v[196:199], v[56:59]
	v_mfma_f32_16x16x32_f16 v[60:63], v[140:143], v[196:199], v[60:63]
	v_mfma_f32_16x16x32_f16 v[64:67], v[144:147], v[196:199], v[64:67]
	s_waitcnt vmcnt(8) lgkmcnt(0)
	s_barrier
	s_add_i32 s35, s32, 0x8000
	s_cmp_lg_u32 s32, 0x18000
	s_cselect_b32 s35, s35, 0
	v_add_u32_e32 v168, s35, v165
	v_add_u32_e32 v169, s35, v164
	v_mfma_f32_16x16x32_f16 v[68:71], v[132:135], v[238:241], v[68:71]
	ds_read_b128 v[148:151], v168 offset:16
	ds_read_b128 v[184:187], v169 offset:16
	v_mfma_f32_16x16x32_f16 v[72:75], v[136:139], v[238:241], v[72:75]
	ds_read_b128 v[152:155], v168 offset:1040
	ds_read_b128 v[188:191], v169 offset:1040
	v_mfma_f32_16x16x32_f16 v[76:79], v[140:143], v[238:241], v[76:79]
	ds_read_b128 v[156:159], v168 offset:2064
	ds_read_b128 v[192:195], v169 offset:2064
	v_mfma_f32_16x16x32_f16 v[80:83], v[144:147], v[238:241], v[80:83]
	ds_read_b128 v[160:163], v168 offset:3088
	ds_read_b128 v[196:199], v169 offset:3088
	v_mfma_f32_16x16x32_f16 v[84:87], v[132:135], v[242:245], v[84:87]
	v_mfma_f32_16x16x32_f16 v[88:91], v[136:139], v[242:245], v[88:91]
	v_mfma_f32_16x16x32_f16 v[92:95], v[140:143], v[242:245], v[92:95]
	v_mfma_f32_16x16x32_f16 v[96:99], v[144:147], v[242:245], v[96:99]
	v_mfma_f32_16x16x32_f16 v[100:103], v[132:135], v[246:249], v[100:103]
	v_mfma_f32_16x16x32_f16 v[104:107], v[136:139], v[246:249], v[104:107]
	v_mfma_f32_16x16x32_f16 v[108:111], v[140:143], v[246:249], v[108:111]
	v_mfma_f32_16x16x32_f16 v[112:115], v[144:147], v[246:249], v[112:115]
	v_mfma_f32_16x16x32_f16 v[116:119], v[132:135], v[250:253], v[116:119]
	v_mfma_f32_16x16x32_f16 v[120:123], v[136:139], v[250:253], v[120:123]
	v_mfma_f32_16x16x32_f16 v[124:127], v[140:143], v[250:253], v[124:127]
	v_mfma_f32_16x16x32_f16 v[128:131], v[144:147], v[250:253], v[128:131]
	s_waitcnt lgkmcnt(0)
	s_mov_b32 s32, s35
	v_add_u32_e32 v169, s32, v164
	v_mfma_f32_16x16x32_f16 v[4:7], v[148:151], v[184:187], v[4:7]
	ds_read_b128 v[238:241], v169 offset:4112
	v_mfma_f32_16x16x32_f16 v[8:11], v[152:155], v[184:187], v[8:11]
	ds_read_b128 v[242:245], v169 offset:5136
	v_mfma_f32_16x16x32_f16 v[12:15], v[156:159], v[184:187], v[12:15]
	ds_read_b128 v[246:249], v169 offset:6160
	v_mfma_f32_16x16x32_f16 v[16:19], v[160:163], v[184:187], v[16:19]
	ds_read_b128 v[250:253], v169 offset:7184
	v_mfma_f32_16x16x32_f16 v[20:23], v[148:151], v[188:191], v[20:23]
	v_mfma_f32_16x16x32_f16 v[24:27], v[152:155], v[188:191], v[24:27]
	v_mfma_f32_16x16x32_f16 v[28:31], v[156:159], v[188:191], v[28:31]
	v_mfma_f32_16x16x32_f16 v[32:35], v[160:163], v[188:191], v[32:35]
	v_mfma_f32_16x16x32_f16 v[36:39], v[148:151], v[192:195], v[36:39]
	v_mfma_f32_16x16x32_f16 v[40:43], v[152:155], v[192:195], v[40:43]
	v_mfma_f32_16x16x32_f16 v[44:47], v[156:159], v[192:195], v[44:47]
	v_mfma_f32_16x16x32_f16 v[48:51], v[160:163], v[192:195], v[48:51]
	v_mfma_f32_16x16x32_f16 v[52:55], v[148:151], v[196:199], v[52:55]
	v_mfma_f32_16x16x32_f16 v[56:59], v[152:155], v[196:199], v[56:59]
	v_mfma_f32_16x16x32_f16 v[60:63], v[156:159], v[196:199], v[60:63]
	v_mfma_f32_16x16x32_f16 v[64:67], v[160:163], v[196:199], v[64:67]
	s_waitcnt vmcnt(4) lgkmcnt(0)
	s_barrier
	s_add_i32 s35, s32, 0x8000
	s_cmp_lg_u32 s32, 0x18000
	s_cselect_b32 s35, s35, 0
	v_add_u32_e32 v168, s35, v165
	v_add_u32_e32 v169, s35, v164
	v_mfma_f32_16x16x32_f16 v[68:71], v[148:151], v[238:241], v[68:71]
	ds_read_b128 v[132:135], v168 offset:16
	ds_read_b128 v[184:187], v169 offset:16
	v_mfma_f32_16x16x32_f16 v[72:75], v[152:155], v[238:241], v[72:75]
	ds_read_b128 v[136:139], v168 offset:1040
	ds_read_b128 v[188:191], v169 offset:1040
	v_mfma_f32_16x16x32_f16 v[76:79], v[156:159], v[238:241], v[76:79]
	ds_read_b128 v[140:143], v168 offset:2064
	ds_read_b128 v[192:195], v169 offset:2064
	v_mfma_f32_16x16x32_f16 v[80:83], v[160:163], v[238:241], v[80:83]
	ds_read_b128 v[144:147], v168 offset:3088
	ds_read_b128 v[196:199], v169 offset:3088
	v_mfma_f32_16x16x32_f16 v[84:87], v[148:151], v[242:245], v[84:87]
	v_mfma_f32_16x16x32_f16 v[88:91], v[152:155], v[242:245], v[88:91]
	v_mfma_f32_16x16x32_f16 v[92:95], v[156:159], v[242:245], v[92:95]
	v_mfma_f32_16x16x32_f16 v[96:99], v[160:163], v[242:245], v[96:99]
	v_mfma_f32_16x16x32_f16 v[100:103], v[148:151], v[246:249], v[100:103]
	v_mfma_f32_16x16x32_f16 v[104:107], v[152:155], v[246:249], v[104:107]
	v_mfma_f32_16x16x32_f16 v[108:111], v[156:159], v[246:249], v[108:111]
	v_mfma_f32_16x16x32_f16 v[112:115], v[160:163], v[246:249], v[112:115]
	v_mfma_f32_16x16x32_f16 v[116:119], v[148:151], v[250:253], v[116:119]
	v_mfma_f32_16x16x32_f16 v[120:123], v[152:155], v[250:253], v[120:123]
	v_mfma_f32_16x16x32_f16 v[124:127], v[156:159], v[250:253], v[124:127]
	v_mfma_f32_16x16x32_f16 v[128:131], v[160:163], v[250:253], v[128:131]
	s_waitcnt lgkmcnt(0)
	s_mov_b32 s32, s35
	v_add_u32_e32 v169, s32, v164
	v_mfma_f32_16x16x32_f16 v[4:7], v[132:135], v[184:187], v[4:7]
	ds_read_b128 v[238:241], v169 offset:4112
	v_mfma_f32_16x16x32_f16 v[8:11], v[136:139], v[184:187], v[8:11]
	ds_read_b128 v[242:245], v169 offset:5136
	v_mfma_f32_16x16x32_f16 v[12:15], v[140:143], v[184:187], v[12:15]
	ds_read_b128 v[246:249], v169 offset:6160
	v_mfma_f32_16x16x32_f16 v[16:19], v[144:147], v[184:187], v[16:19]
	ds_read_b128 v[250:253], v169 offset:7184
	v_mfma_f32_16x16x32_f16 v[20:23], v[132:135], v[188:191], v[20:23]
	v_mfma_f32_16x16x32_f16 v[24:27], v[136:139], v[188:191], v[24:27]
	v_mfma_f32_16x16x32_f16 v[28:31], v[140:143], v[188:191], v[28:31]
	v_mfma_f32_16x16x32_f16 v[32:35], v[144:147], v[188:191], v[32:35]
	v_mfma_f32_16x16x32_f16 v[36:39], v[132:135], v[192:195], v[36:39]
	v_mfma_f32_16x16x32_f16 v[40:43], v[136:139], v[192:195], v[40:43]
	v_mfma_f32_16x16x32_f16 v[44:47], v[140:143], v[192:195], v[44:47]
	v_mfma_f32_16x16x32_f16 v[48:51], v[144:147], v[192:195], v[48:51]
	v_mfma_f32_16x16x32_f16 v[52:55], v[132:135], v[196:199], v[52:55]
	v_mfma_f32_16x16x32_f16 v[56:59], v[136:139], v[196:199], v[56:59]
	v_mfma_f32_16x16x32_f16 v[60:63], v[140:143], v[196:199], v[60:63]
	v_mfma_f32_16x16x32_f16 v[64:67], v[144:147], v[196:199], v[64:67]
	s_waitcnt vmcnt(0) lgkmcnt(0)
	s_barrier
	s_add_i32 s35, s32, 0x8000
	s_cmp_lg_u32 s32, 0x18000
	s_cselect_b32 s35, s35, 0
	v_add_u32_e32 v168, s35, v165
	v_add_u32_e32 v169, s35, v164
	v_mfma_f32_16x16x32_f16 v[68:71], v[132:135], v[238:241], v[68:71]
	ds_read_b128 v[148:151], v168 offset:16
	ds_read_b128 v[184:187], v169 offset:16
	v_mfma_f32_16x16x32_f16 v[72:75], v[136:139], v[238:241], v[72:75]
	ds_read_b128 v[152:155], v168 offset:1040
	ds_read_b128 v[188:191], v169 offset:1040
	v_mfma_f32_16x16x32_f16 v[76:79], v[140:143], v[238:241], v[76:79]
	ds_read_b128 v[156:159], v168 offset:2064
	ds_read_b128 v[192:195], v169 offset:2064
	v_mfma_f32_16x16x32_f16 v[80:83], v[144:147], v[238:241], v[80:83]
	ds_read_b128 v[160:163], v168 offset:3088
	ds_read_b128 v[196:199], v169 offset:3088
	v_mfma_f32_16x16x32_f16 v[84:87], v[132:135], v[242:245], v[84:87]
	v_mfma_f32_16x16x32_f16 v[88:91], v[136:139], v[242:245], v[88:91]
	v_mfma_f32_16x16x32_f16 v[92:95], v[140:143], v[242:245], v[92:95]
	v_mfma_f32_16x16x32_f16 v[96:99], v[144:147], v[242:245], v[96:99]
	v_mfma_f32_16x16x32_f16 v[100:103], v[132:135], v[246:249], v[100:103]
	v_mfma_f32_16x16x32_f16 v[104:107], v[136:139], v[246:249], v[104:107]
	v_mfma_f32_16x16x32_f16 v[108:111], v[140:143], v[246:249], v[108:111]
	v_mfma_f32_16x16x32_f16 v[112:115], v[144:147], v[246:249], v[112:115]
	v_mfma_f32_16x16x32_f16 v[116:119], v[132:135], v[250:253], v[116:119]
	v_mfma_f32_16x16x32_f16 v[120:123], v[136:139], v[250:253], v[120:123]
	v_mfma_f32_16x16x32_f16 v[124:127], v[140:143], v[250:253], v[124:127]
	v_mfma_f32_16x16x32_f16 v[128:131], v[144:147], v[250:253], v[128:131]
	s_waitcnt lgkmcnt(0)
	s_mov_b32 s32, s35
	v_add_u32_e32 v169, s32, v164
	v_mfma_f32_16x16x32_f16 v[4:7], v[148:151], v[184:187], v[4:7]
	ds_read_b128 v[238:241], v169 offset:4112
	v_mfma_f32_16x16x32_f16 v[8:11], v[152:155], v[184:187], v[8:11]
	ds_read_b128 v[242:245], v169 offset:5136
	v_mfma_f32_16x16x32_f16 v[12:15], v[156:159], v[184:187], v[12:15]
	ds_read_b128 v[246:249], v169 offset:6160
	v_mfma_f32_16x16x32_f16 v[16:19], v[160:163], v[184:187], v[16:19]
	ds_read_b128 v[250:253], v169 offset:7184
	v_mfma_f32_16x16x32_f16 v[20:23], v[148:151], v[188:191], v[20:23]
	v_mfma_f32_16x16x32_f16 v[24:27], v[152:155], v[188:191], v[24:27]
	v_mfma_f32_16x16x32_f16 v[28:31], v[156:159], v[188:191], v[28:31]
	v_mfma_f32_16x16x32_f16 v[32:35], v[160:163], v[188:191], v[32:35]
	v_mfma_f32_16x16x32_f16 v[36:39], v[148:151], v[192:195], v[36:39]
	v_mfma_f32_16x16x32_f16 v[40:43], v[152:155], v[192:195], v[40:43]
	v_mfma_f32_16x16x32_f16 v[44:47], v[156:159], v[192:195], v[44:47]
	v_mfma_f32_16x16x32_f16 v[48:51], v[160:163], v[192:195], v[48:51]
	v_mfma_f32_16x16x32_f16 v[52:55], v[148:151], v[196:199], v[52:55]
	v_mfma_f32_16x16x32_f16 v[56:59], v[152:155], v[196:199], v[56:59]
	v_mfma_f32_16x16x32_f16 v[60:63], v[156:159], v[196:199], v[60:63]
	v_mfma_f32_16x16x32_f16 v[64:67], v[160:163], v[196:199], v[64:67]
	s_waitcnt lgkmcnt(0)
	s_barrier
	v_mfma_f32_16x16x32_f16 v[68:71], v[148:151], v[238:241], v[68:71]
	v_mfma_f32_16x16x32_f16 v[72:75], v[152:155], v[238:241], v[72:75]
	v_mfma_f32_16x16x32_f16 v[76:79], v[156:159], v[238:241], v[76:79]
	v_mfma_f32_16x16x32_f16 v[80:83], v[160:163], v[238:241], v[80:83]
	v_mfma_f32_16x16x32_f16 v[84:87], v[148:151], v[242:245], v[84:87]
	v_mfma_f32_16x16x32_f16 v[88:91], v[152:155], v[242:245], v[88:91]
	v_mfma_f32_16x16x32_f16 v[92:95], v[156:159], v[242:245], v[92:95]
	v_mfma_f32_16x16x32_f16 v[96:99], v[160:163], v[242:245], v[96:99]
	v_mfma_f32_16x16x32_f16 v[100:103], v[148:151], v[246:249], v[100:103]
	v_mfma_f32_16x16x32_f16 v[104:107], v[152:155], v[246:249], v[104:107]
	v_mfma_f32_16x16x32_f16 v[108:111], v[156:159], v[246:249], v[108:111]
	v_mfma_f32_16x16x32_f16 v[112:115], v[160:163], v[246:249], v[112:115]
	v_mfma_f32_16x16x32_f16 v[116:119], v[148:151], v[250:253], v[116:119]
	v_mfma_f32_16x16x32_f16 v[120:123], v[152:155], v[250:253], v[120:123]
	v_mfma_f32_16x16x32_f16 v[124:127], v[156:159], v[250:253], v[124:127]
	v_mfma_f32_16x16x32_f16 v[128:131], v[160:163], v[250:253], v[128:131]
	s_sub_u32 s77, s34, 0x1000
	s_lshr_b32 s77, s77, 12
	s_add_u32 s77, s77, 1
	s_cmp_lt_u32 s34, 0x1000
	s_cselect_b32 s77, 0, s77
	s_mul_i32 s77, s77, 0x6000
	s_add_u32 s68, s44, s77
	s_addc_u32 s69, s45, 0
	s_add_u32 s68, s68, 0xfa10600
	s_addc_u32 s69, s69, 0
	s_lshl_b32 s82, s34, 11
	s_add_u32 s80, s46, s82
	s_addc_u32 s81, s47, 0
	s_lshl_b32 s82, s30, 1
	s_add_u32 s80, s80, s82
	s_addc_u32 s81, s81, 0
	v_and_b32_e32 v172, 15, v200
	v_bfe_u32 v173, v200, 4, 2
	v_bfe_u32 v174, v200, 6, 2
	v_bfe_u32 v175, v200, 8, 1
	v_lshlrev_b32_e32 v176, 6, v174
	v_lshl_or_b32 v176, v173, 2, v176
	v_lshl_or_b32 v175, v175, 7, v172
	v_lshlrev_b32_e32 v175, 11, v175
	v_lshl_add_u32 v177, v176, 1, v175
	v_add_u32_e32 v176, s30, v176
	v_lshlrev_b32_e32 v176, 2, v176
	global_load_dwordx4 v[132:135], v176, s[68:69]
	global_load_dwordx4 v[136:139], v176, s[68:69] offset:64
	global_load_dwordx4 v[140:143], v176, s[68:69] offset:128
	global_load_dwordx4 v[144:147], v176, s[68:69] offset:192
	v_mov_b32_e32 v178, v177
	global_load_dwordx2 v[184:185], v178, s[80:81]
	global_load_dwordx2 v[186:187], v178, s[80:81] offset:32
	global_load_dwordx2 v[188:189], v178, s[80:81] offset:64
	global_load_dwordx2 v[190:191], v178, s[80:81] offset:96
	v_add_u32_e32 v178, 0x8000, v178
	global_load_dwordx2 v[238:239], v178, s[80:81]
	global_load_dwordx2 v[240:241], v178, s[80:81] offset:32
	global_load_dwordx2 v[242:243], v178, s[80:81] offset:64
	global_load_dwordx2 v[244:245], v178, s[80:81] offset:96
	s_waitcnt vmcnt(7)
	v_cvt_f32_f16_e32 v164, v184
	v_cvt_f32_f16_sdwa v165, v184 dst_sel:DWORD dst_unused:UNUSED_PAD src0_sel:WORD_1
	v_cvt_f32_f16_e32 v166, v185
	v_cvt_f32_f16_sdwa v167, v185 dst_sel:DWORD dst_unused:UNUSED_PAD src0_sel:WORD_1
	v_pk_mul_f32 v[164:165], v[164:165], s[84:85] op_sel_hi:[1,0]
	v_pk_mul_f32 v[166:167], v[166:167], s[84:85] op_sel_hi:[1,0]
	v_pk_fma_f32 v[4:5], v[4:5], v[132:133], v[164:165]
	v_pk_fma_f32 v[6:7], v[6:7], v[134:135], v[166:167]
	v_cvt_pk_f16_f32 v172, v4, v5
	v_cvt_pk_f16_f32 v173, v6, v7
	global_store_dwordx2 v177, v[172:173], s[80:81]
	s_waitcnt vmcnt(7)
	v_cvt_f32_f16_e32 v164, v186
	v_cvt_f32_f16_sdwa v165, v186 dst_sel:DWORD dst_unused:UNUSED_PAD src0_sel:WORD_1
	v_cvt_f32_f16_e32 v166, v187
	v_cvt_f32_f16_sdwa v167, v187 dst_sel:DWORD dst_unused:UNUSED_PAD src0_sel:WORD_1
	v_pk_mul_f32 v[164:165], v[164:165], s[84:85] op_sel_hi:[1,0]
	v_pk_mul_f32 v[166:167], v[166:167], s[84:85] op_sel_hi:[1,0]
	v_pk_fma_f32 v[8:9], v[8:9], v[136:137], v[164:165]
	v_pk_fma_f32 v[10:11], v[10:11], v[138:139], v[166:167]
	v_cvt_pk_f16_f32 v174, v8, v9
	v_cvt_pk_f16_f32 v175, v10, v11
	global_store_dwordx2 v177, v[174:175], s[80:81] offset:32
	s_waitcnt vmcnt(7)
	v_cvt_f32_f16_e32 v164, v188
	v_cvt_f32_f16_sdwa v165, v188 dst_sel:DWORD dst_unused:UNUSED_PAD src0_sel:WORD_1
	v_cvt_f32_f16_e32 v166, v189
	v_cvt_f32_f16_sdwa v167, v189 dst_sel:DWORD dst_unused:UNUSED_PAD src0_sel:WORD_1
	v_pk_mul_f32 v[164:165], v[164:165], s[84:85] op_sel_hi:[1,0]
	v_pk_mul_f32 v[166:167], v[166:167], s[84:85] op_sel_hi:[1,0]
	v_pk_fma_f32 v[12:13], v[12:13], v[140:141], v[164:165]
	v_pk_fma_f32 v[14:15], v[14:15], v[142:143], v[166:167]
	v_cvt_pk_f16_f32 v172, v12, v13
	v_cvt_pk_f16_f32 v173, v14, v15
	global_store_dwordx2 v177, v[172:173], s[80:81] offset:64
	s_waitcnt vmcnt(7)
	v_cvt_f32_f16_e32 v164, v190
	v_cvt_f32_f16_sdwa v165, v190 dst_sel:DWORD dst_unused:UNUSED_PAD src0_sel:WORD_1
	v_cvt_f32_f16_e32 v166, v191
	v_cvt_f32_f16_sdwa v167, v191 dst_sel:DWORD dst_unused:UNUSED_PAD src0_sel:WORD_1
	v_pk_mul_f32 v[164:165], v[164:165], s[84:85] op_sel_hi:[1,0]
	v_pk_mul_f32 v[166:167], v[166:167], s[84:85] op_sel_hi:[1,0]
	v_pk_fma_f32 v[16:17], v[16:17], v[144:145], v[164:165]
	v_pk_fma_f32 v[18:19], v[18:19], v[146:147], v[166:167]
	v_cvt_pk_f16_f32 v174, v16, v17
	v_cvt_pk_f16_f32 v175, v18, v19
	global_store_dwordx2 v177, v[174:175], s[80:81] offset:96
	v_add_u32_e32 v177, 0x8000, v177
	v_add_u32_e32 v178, 0x8000, v178
	global_load_dwordx2 v[184:185], v178, s[80:81]
	global_load_dwordx2 v[186:187], v178, s[80:81] offset:32
	global_load_dwordx2 v[188:189], v178, s[80:81] offset:64
	global_load_dwordx2 v[190:191], v178, s[80:81] offset:96
	s_waitcnt vmcnt(11)
	v_cvt_f32_f16_e32 v164, v238
	v_cvt_f32_f16_sdwa v165, v238 dst_sel:DWORD dst_unused:UNUSED_PAD src0_sel:WORD_1
	v_cvt_f32_f16_e32 v166, v239
	v_cvt_f32_f16_sdwa v167, v239 dst_sel:DWORD dst_unused:UNUSED_PAD src0_sel:WORD_1
	v_pk_mul_f32 v[164:165], v[164:165], s[84:85] op_sel_hi:[1,0]
	v_pk_mul_f32 v[166:167], v[166:167], s[84:85] op_sel_hi:[1,0]
	v_pk_fma_f32 v[20:21], v[20:21], v[132:133], v[164:165]
	v_pk_fma_f32 v[22:23], v[22:23], v[134:135], v[166:167]
	v_cvt_pk_f16_f32 v172, v20, v21
	v_cvt_pk_f16_f32 v173, v22, v23
	global_store_dwordx2 v177, v[172:173], s[80:81]
	s_waitcnt vmcnt(11)
	v_cvt_f32_f16_e32 v164, v240
	v_cvt_f32_f16_sdwa v165, v240 dst_sel:DWORD dst_unused:UNUSED_PAD src0_sel:WORD_1
	v_cvt_f32_f16_e32 v166, v241
	v_cvt_f32_f16_sdwa v167, v241 dst_sel:DWORD dst_unused:UNUSED_PAD src0_sel:WORD_1
	v_pk_mul_f32 v[164:165], v[164:165], s[84:85] op_sel_hi:[1,0]
	v_pk_mul_f32 v[166:167], v[166:167], s[84:85] op_sel_hi:[1,0]
	v_pk_fma_f32 v[24:25], v[24:25], v[136:137], v[164:165]
	v_pk_fma_f32 v[26:27], v[26:27], v[138:139], v[166:167]
	v_cvt_pk_f16_f32 v174, v24, v25
	v_cvt_pk_f16_f32 v175, v26, v27
	global_store_dwordx2 v177, v[174:175], s[80:81] offset:32
	s_waitcnt vmcnt(11)
	v_cvt_f32_f16_e32 v164, v242
	v_cvt_f32_f16_sdwa v165, v242 dst_sel:DWORD dst_unused:UNUSED_PAD src0_sel:WORD_1
	v_cvt_f32_f16_e32 v166, v243
	v_cvt_f32_f16_sdwa v167, v243 dst_sel:DWORD dst_unused:UNUSED_PAD src0_sel:WORD_1
	v_pk_mul_f32 v[164:165], v[164:165], s[84:85] op_sel_hi:[1,0]
	v_pk_mul_f32 v[166:167], v[166:167], s[84:85] op_sel_hi:[1,0]
	v_pk_fma_f32 v[28:29], v[28:29], v[140:141], v[164:165]
	v_pk_fma_f32 v[30:31], v[30:31], v[142:143], v[166:167]
	v_cvt_pk_f16_f32 v172, v28, v29
	v_cvt_pk_f16_f32 v173, v30, v31
	global_store_dwordx2 v177, v[172:173], s[80:81] offset:64
	s_waitcnt vmcnt(11)
	v_cvt_f32_f16_e32 v164, v244
	v_cvt_f32_f16_sdwa v165, v244 dst_sel:DWORD dst_unused:UNUSED_PAD src0_sel:WORD_1
	v_cvt_f32_f16_e32 v166, v245
	v_cvt_f32_f16_sdwa v167, v245 dst_sel:DWORD dst_unused:UNUSED_PAD src0_sel:WORD_1
	v_pk_mul_f32 v[164:165], v[164:165], s[84:85] op_sel_hi:[1,0]
	v_pk_mul_f32 v[166:167], v[166:167], s[84:85] op_sel_hi:[1,0]
	v_pk_fma_f32 v[32:33], v[32:33], v[144:145], v[164:165]
	v_pk_fma_f32 v[34:35], v[34:35], v[146:147], v[166:167]
	v_cvt_pk_f16_f32 v174, v32, v33
	v_cvt_pk_f16_f32 v175, v34, v35
	global_store_dwordx2 v177, v[174:175], s[80:81] offset:96
	v_add_u32_e32 v177, 0x8000, v177
	v_add_u32_e32 v178, 0x8000, v178
	global_load_dwordx2 v[238:239], v178, s[80:81]
	global_load_dwordx2 v[240:241], v178, s[80:81] offset:32
	global_load_dwordx2 v[242:243], v178, s[80:81] offset:64
	global_load_dwordx2 v[244:245], v178, s[80:81] offset:96
	s_waitcnt vmcnt(11)
	v_cvt_f32_f16_e32 v164, v184
	v_cvt_f32_f16_sdwa v165, v184 dst_sel:DWORD dst_unused:UNUSED_PAD src0_sel:WORD_1
	v_cvt_f32_f16_e32 v166, v185
	v_cvt_f32_f16_sdwa v167, v185 dst_sel:DWORD dst_unused:UNUSED_PAD src0_sel:WORD_1
	v_pk_mul_f32 v[164:165], v[164:165], s[84:85] op_sel_hi:[1,0]
	v_pk_mul_f32 v[166:167], v[166:167], s[84:85] op_sel_hi:[1,0]
	v_pk_fma_f32 v[36:37], v[36:37], v[132:133], v[164:165]
	v_pk_fma_f32 v[38:39], v[38:39], v[134:135], v[166:167]
	v_cvt_pk_f16_f32 v172, v36, v37
	v_cvt_pk_f16_f32 v173, v38, v39
	global_store_dwordx2 v177, v[172:173], s[80:81]
	s_waitcnt vmcnt(11)
	v_cvt_f32_f16_e32 v164, v186
	v_cvt_f32_f16_sdwa v165, v186 dst_sel:DWORD dst_unused:UNUSED_PAD src0_sel:WORD_1
	v_cvt_f32_f16_e32 v166, v187
	v_cvt_f32_f16_sdwa v167, v187 dst_sel:DWORD dst_unused:UNUSED_PAD src0_sel:WORD_1
	v_pk_mul_f32 v[164:165], v[164:165], s[84:85] op_sel_hi:[1,0]
	v_pk_mul_f32 v[166:167], v[166:167], s[84:85] op_sel_hi:[1,0]
	v_pk_fma_f32 v[40:41], v[40:41], v[136:137], v[164:165]
	v_pk_fma_f32 v[42:43], v[42:43], v[138:139], v[166:167]
	v_cvt_pk_f16_f32 v174, v40, v41
	v_cvt_pk_f16_f32 v175, v42, v43
	global_store_dwordx2 v177, v[174:175], s[80:81] offset:32
	s_waitcnt vmcnt(11)
	v_cvt_f32_f16_e32 v164, v188
	v_cvt_f32_f16_sdwa v165, v188 dst_sel:DWORD dst_unused:UNUSED_PAD src0_sel:WORD_1
	v_cvt_f32_f16_e32 v166, v189
	v_cvt_f32_f16_sdwa v167, v189 dst_sel:DWORD dst_unused:UNUSED_PAD src0_sel:WORD_1
	v_pk_mul_f32 v[164:165], v[164:165], s[84:85] op_sel_hi:[1,0]
	v_pk_mul_f32 v[166:167], v[166:167], s[84:85] op_sel_hi:[1,0]
	v_pk_fma_f32 v[44:45], v[44:45], v[140:141], v[164:165]
	v_pk_fma_f32 v[46:47], v[46:47], v[142:143], v[166:167]
	v_cvt_pk_f16_f32 v172, v44, v45
	v_cvt_pk_f16_f32 v173, v46, v47
	global_store_dwordx2 v177, v[172:173], s[80:81] offset:64
	s_waitcnt vmcnt(11)
	v_cvt_f32_f16_e32 v164, v190
	v_cvt_f32_f16_sdwa v165, v190 dst_sel:DWORD dst_unused:UNUSED_PAD src0_sel:WORD_1
	v_cvt_f32_f16_e32 v166, v191
	v_cvt_f32_f16_sdwa v167, v191 dst_sel:DWORD dst_unused:UNUSED_PAD src0_sel:WORD_1
	v_pk_mul_f32 v[164:165], v[164:165], s[84:85] op_sel_hi:[1,0]
	v_pk_mul_f32 v[166:167], v[166:167], s[84:85] op_sel_hi:[1,0]
	v_pk_fma_f32 v[48:49], v[48:49], v[144:145], v[164:165]
	v_pk_fma_f32 v[50:51], v[50:51], v[146:147], v[166:167]
	v_cvt_pk_f16_f32 v174, v48, v49
	v_cvt_pk_f16_f32 v175, v50, v51
	global_store_dwordx2 v177, v[174:175], s[80:81] offset:96
	v_add_u32_e32 v177, 0x8000, v177
	v_add_u32_e32 v178, 0x8000, v178
	global_load_dwordx2 v[184:185], v178, s[80:81]
	global_load_dwordx2 v[186:187], v178, s[80:81] offset:32
	global_load_dwordx2 v[188:189], v178, s[80:81] offset:64
	global_load_dwordx2 v[190:191], v178, s[80:81] offset:96
	s_waitcnt vmcnt(11)
	v_cvt_f32_f16_e32 v164, v238
	v_cvt_f32_f16_sdwa v165, v238 dst_sel:DWORD dst_unused:UNUSED_PAD src0_sel:WORD_1
	v_cvt_f32_f16_e32 v166, v239
	v_cvt_f32_f16_sdwa v167, v239 dst_sel:DWORD dst_unused:UNUSED_PAD src0_sel:WORD_1
	v_pk_mul_f32 v[164:165], v[164:165], s[84:85] op_sel_hi:[1,0]
	v_pk_mul_f32 v[166:167], v[166:167], s[84:85] op_sel_hi:[1,0]
	v_pk_fma_f32 v[52:53], v[52:53], v[132:133], v[164:165]
	v_pk_fma_f32 v[54:55], v[54:55], v[134:135], v[166:167]
	v_cvt_pk_f16_f32 v172, v52, v53
	v_cvt_pk_f16_f32 v173, v54, v55
	global_store_dwordx2 v177, v[172:173], s[80:81]
	s_waitcnt vmcnt(11)
	v_cvt_f32_f16_e32 v164, v240
	v_cvt_f32_f16_sdwa v165, v240 dst_sel:DWORD dst_unused:UNUSED_PAD src0_sel:WORD_1
	v_cvt_f32_f16_e32 v166, v241
	v_cvt_f32_f16_sdwa v167, v241 dst_sel:DWORD dst_unused:UNUSED_PAD src0_sel:WORD_1
	v_pk_mul_f32 v[164:165], v[164:165], s[84:85] op_sel_hi:[1,0]
	v_pk_mul_f32 v[166:167], v[166:167], s[84:85] op_sel_hi:[1,0]
	v_pk_fma_f32 v[56:57], v[56:57], v[136:137], v[164:165]
	v_pk_fma_f32 v[58:59], v[58:59], v[138:139], v[166:167]
	v_cvt_pk_f16_f32 v174, v56, v57
	v_cvt_pk_f16_f32 v175, v58, v59
	global_store_dwordx2 v177, v[174:175], s[80:81] offset:32
	s_waitcnt vmcnt(11)
	v_cvt_f32_f16_e32 v164, v242
	v_cvt_f32_f16_sdwa v165, v242 dst_sel:DWORD dst_unused:UNUSED_PAD src0_sel:WORD_1
	v_cvt_f32_f16_e32 v166, v243
	v_cvt_f32_f16_sdwa v167, v243 dst_sel:DWORD dst_unused:UNUSED_PAD src0_sel:WORD_1
	v_pk_mul_f32 v[164:165], v[164:165], s[84:85] op_sel_hi:[1,0]
	v_pk_mul_f32 v[166:167], v[166:167], s[84:85] op_sel_hi:[1,0]
	v_pk_fma_f32 v[60:61], v[60:61], v[140:141], v[164:165]
	v_pk_fma_f32 v[62:63], v[62:63], v[142:143], v[166:167]
	v_cvt_pk_f16_f32 v172, v60, v61
	v_cvt_pk_f16_f32 v173, v62, v63
	global_store_dwordx2 v177, v[172:173], s[80:81] offset:64
	s_waitcnt vmcnt(11)
	v_cvt_f32_f16_e32 v164, v244
	v_cvt_f32_f16_sdwa v165, v244 dst_sel:DWORD dst_unused:UNUSED_PAD src0_sel:WORD_1
	v_cvt_f32_f16_e32 v166, v245
	v_cvt_f32_f16_sdwa v167, v245 dst_sel:DWORD dst_unused:UNUSED_PAD src0_sel:WORD_1
	v_pk_mul_f32 v[164:165], v[164:165], s[84:85] op_sel_hi:[1,0]
	v_pk_mul_f32 v[166:167], v[166:167], s[84:85] op_sel_hi:[1,0]
	v_pk_fma_f32 v[64:65], v[64:65], v[144:145], v[164:165]
	v_pk_fma_f32 v[66:67], v[66:67], v[146:147], v[166:167]
	v_cvt_pk_f16_f32 v174, v64, v65
	v_cvt_pk_f16_f32 v175, v66, v67
	global_store_dwordx2 v177, v[174:175], s[80:81] offset:96
	v_add_u32_e32 v177, 0x8000, v177
	v_add_u32_e32 v178, 0x8000, v178
	global_load_dwordx2 v[238:239], v178, s[80:81]
	global_load_dwordx2 v[240:241], v178, s[80:81] offset:32
	global_load_dwordx2 v[242:243], v178, s[80:81] offset:64
	global_load_dwordx2 v[244:245], v178, s[80:81] offset:96
	s_waitcnt vmcnt(11)
	v_cvt_f32_f16_e32 v164, v184
	v_cvt_f32_f16_sdwa v165, v184 dst_sel:DWORD dst_unused:UNUSED_PAD src0_sel:WORD_1
	v_cvt_f32_f16_e32 v166, v185
	v_cvt_f32_f16_sdwa v167, v185 dst_sel:DWORD dst_unused:UNUSED_PAD src0_sel:WORD_1
	v_pk_mul_f32 v[164:165], v[164:165], s[84:85] op_sel_hi:[1,0]
	v_pk_mul_f32 v[166:167], v[166:167], s[84:85] op_sel_hi:[1,0]
	v_pk_fma_f32 v[68:69], v[68:69], v[132:133], v[164:165]
	v_pk_fma_f32 v[70:71], v[70:71], v[134:135], v[166:167]
	v_cvt_pk_f16_f32 v172, v68, v69
	v_cvt_pk_f16_f32 v173, v70, v71
	global_store_dwordx2 v177, v[172:173], s[80:81]
	s_waitcnt vmcnt(11)
	v_cvt_f32_f16_e32 v164, v186
	v_cvt_f32_f16_sdwa v165, v186 dst_sel:DWORD dst_unused:UNUSED_PAD src0_sel:WORD_1
	v_cvt_f32_f16_e32 v166, v187
	v_cvt_f32_f16_sdwa v167, v187 dst_sel:DWORD dst_unused:UNUSED_PAD src0_sel:WORD_1
	v_pk_mul_f32 v[164:165], v[164:165], s[84:85] op_sel_hi:[1,0]
	v_pk_mul_f32 v[166:167], v[166:167], s[84:85] op_sel_hi:[1,0]
	v_pk_fma_f32 v[72:73], v[72:73], v[136:137], v[164:165]
	v_pk_fma_f32 v[74:75], v[74:75], v[138:139], v[166:167]
	v_cvt_pk_f16_f32 v174, v72, v73
	v_cvt_pk_f16_f32 v175, v74, v75
	global_store_dwordx2 v177, v[174:175], s[80:81] offset:32
	s_waitcnt vmcnt(11)
	v_cvt_f32_f16_e32 v164, v188
	v_cvt_f32_f16_sdwa v165, v188 dst_sel:DWORD dst_unused:UNUSED_PAD src0_sel:WORD_1
	v_cvt_f32_f16_e32 v166, v189
	v_cvt_f32_f16_sdwa v167, v189 dst_sel:DWORD dst_unused:UNUSED_PAD src0_sel:WORD_1
	v_pk_mul_f32 v[164:165], v[164:165], s[84:85] op_sel_hi:[1,0]
	v_pk_mul_f32 v[166:167], v[166:167], s[84:85] op_sel_hi:[1,0]
	v_pk_fma_f32 v[76:77], v[76:77], v[140:141], v[164:165]
	v_pk_fma_f32 v[78:79], v[78:79], v[142:143], v[166:167]
	v_cvt_pk_f16_f32 v172, v76, v77
	v_cvt_pk_f16_f32 v173, v78, v79
	global_store_dwordx2 v177, v[172:173], s[80:81] offset:64
	s_waitcnt vmcnt(11)
	v_cvt_f32_f16_e32 v164, v190
	v_cvt_f32_f16_sdwa v165, v190 dst_sel:DWORD dst_unused:UNUSED_PAD src0_sel:WORD_1
	v_cvt_f32_f16_e32 v166, v191
	v_cvt_f32_f16_sdwa v167, v191 dst_sel:DWORD dst_unused:UNUSED_PAD src0_sel:WORD_1
	v_pk_mul_f32 v[164:165], v[164:165], s[84:85] op_sel_hi:[1,0]
	v_pk_mul_f32 v[166:167], v[166:167], s[84:85] op_sel_hi:[1,0]
	v_pk_fma_f32 v[80:81], v[80:81], v[144:145], v[164:165]
	v_pk_fma_f32 v[82:83], v[82:83], v[146:147], v[166:167]
	v_cvt_pk_f16_f32 v174, v80, v81
	v_cvt_pk_f16_f32 v175, v82, v83
	global_store_dwordx2 v177, v[174:175], s[80:81] offset:96
	v_add_u32_e32 v177, 0x8000, v177
	v_add_u32_e32 v178, 0x8000, v178
	global_load_dwordx2 v[184:185], v178, s[80:81]
	global_load_dwordx2 v[186:187], v178, s[80:81] offset:32
	global_load_dwordx2 v[188:189], v178, s[80:81] offset:64
	global_load_dwordx2 v[190:191], v178, s[80:81] offset:96
	s_waitcnt vmcnt(11)
	v_cvt_f32_f16_e32 v164, v238
	v_cvt_f32_f16_sdwa v165, v238 dst_sel:DWORD dst_unused:UNUSED_PAD src0_sel:WORD_1
	v_cvt_f32_f16_e32 v166, v239
	v_cvt_f32_f16_sdwa v167, v239 dst_sel:DWORD dst_unused:UNUSED_PAD src0_sel:WORD_1
	v_pk_mul_f32 v[164:165], v[164:165], s[84:85] op_sel_hi:[1,0]
	v_pk_mul_f32 v[166:167], v[166:167], s[84:85] op_sel_hi:[1,0]
	v_pk_fma_f32 v[84:85], v[84:85], v[132:133], v[164:165]
	v_pk_fma_f32 v[86:87], v[86:87], v[134:135], v[166:167]
	v_cvt_pk_f16_f32 v172, v84, v85
	v_cvt_pk_f16_f32 v173, v86, v87
	global_store_dwordx2 v177, v[172:173], s[80:81]
	s_waitcnt vmcnt(11)
	v_cvt_f32_f16_e32 v164, v240
	v_cvt_f32_f16_sdwa v165, v240 dst_sel:DWORD dst_unused:UNUSED_PAD src0_sel:WORD_1
	v_cvt_f32_f16_e32 v166, v241
	v_cvt_f32_f16_sdwa v167, v241 dst_sel:DWORD dst_unused:UNUSED_PAD src0_sel:WORD_1
	v_pk_mul_f32 v[164:165], v[164:165], s[84:85] op_sel_hi:[1,0]
	v_pk_mul_f32 v[166:167], v[166:167], s[84:85] op_sel_hi:[1,0]
	v_pk_fma_f32 v[88:89], v[88:89], v[136:137], v[164:165]
	v_pk_fma_f32 v[90:91], v[90:91], v[138:139], v[166:167]
	v_cvt_pk_f16_f32 v174, v88, v89
	v_cvt_pk_f16_f32 v175, v90, v91
	global_store_dwordx2 v177, v[174:175], s[80:81] offset:32
	s_waitcnt vmcnt(11)
	v_cvt_f32_f16_e32 v164, v242
	v_cvt_f32_f16_sdwa v165, v242 dst_sel:DWORD dst_unused:UNUSED_PAD src0_sel:WORD_1
	v_cvt_f32_f16_e32 v166, v243
	v_cvt_f32_f16_sdwa v167, v243 dst_sel:DWORD dst_unused:UNUSED_PAD src0_sel:WORD_1
	v_pk_mul_f32 v[164:165], v[164:165], s[84:85] op_sel_hi:[1,0]
	v_pk_mul_f32 v[166:167], v[166:167], s[84:85] op_sel_hi:[1,0]
	v_pk_fma_f32 v[92:93], v[92:93], v[140:141], v[164:165]
	v_pk_fma_f32 v[94:95], v[94:95], v[142:143], v[166:167]
	v_cvt_pk_f16_f32 v172, v92, v93
	v_cvt_pk_f16_f32 v173, v94, v95
	global_store_dwordx2 v177, v[172:173], s[80:81] offset:64
	s_waitcnt vmcnt(11)
	v_cvt_f32_f16_e32 v164, v244
	v_cvt_f32_f16_sdwa v165, v244 dst_sel:DWORD dst_unused:UNUSED_PAD src0_sel:WORD_1
	v_cvt_f32_f16_e32 v166, v245
	v_cvt_f32_f16_sdwa v167, v245 dst_sel:DWORD dst_unused:UNUSED_PAD src0_sel:WORD_1
	v_pk_mul_f32 v[164:165], v[164:165], s[84:85] op_sel_hi:[1,0]
	v_pk_mul_f32 v[166:167], v[166:167], s[84:85] op_sel_hi:[1,0]
	v_pk_fma_f32 v[96:97], v[96:97], v[144:145], v[164:165]
	v_pk_fma_f32 v[98:99], v[98:99], v[146:147], v[166:167]
	v_cvt_pk_f16_f32 v174, v96, v97
	v_cvt_pk_f16_f32 v175, v98, v99
	global_store_dwordx2 v177, v[174:175], s[80:81] offset:96
	v_add_u32_e32 v177, 0x8000, v177
	v_add_u32_e32 v178, 0x8000, v178
	global_load_dwordx2 v[238:239], v178, s[80:81]
	global_load_dwordx2 v[240:241], v178, s[80:81] offset:32
	global_load_dwordx2 v[242:243], v178, s[80:81] offset:64
	global_load_dwordx2 v[244:245], v178, s[80:81] offset:96
	s_waitcnt vmcnt(11)
	v_cvt_f32_f16_e32 v164, v184
	v_cvt_f32_f16_sdwa v165, v184 dst_sel:DWORD dst_unused:UNUSED_PAD src0_sel:WORD_1
	v_cvt_f32_f16_e32 v166, v185
	v_cvt_f32_f16_sdwa v167, v185 dst_sel:DWORD dst_unused:UNUSED_PAD src0_sel:WORD_1
	v_pk_mul_f32 v[164:165], v[164:165], s[84:85] op_sel_hi:[1,0]
	v_pk_mul_f32 v[166:167], v[166:167], s[84:85] op_sel_hi:[1,0]
	v_pk_fma_f32 v[100:101], v[100:101], v[132:133], v[164:165]
	v_pk_fma_f32 v[102:103], v[102:103], v[134:135], v[166:167]
	v_cvt_pk_f16_f32 v172, v100, v101
	v_cvt_pk_f16_f32 v173, v102, v103
	global_store_dwordx2 v177, v[172:173], s[80:81]
	s_waitcnt vmcnt(11)
	v_cvt_f32_f16_e32 v164, v186
	v_cvt_f32_f16_sdwa v165, v186 dst_sel:DWORD dst_unused:UNUSED_PAD src0_sel:WORD_1
	v_cvt_f32_f16_e32 v166, v187
	v_cvt_f32_f16_sdwa v167, v187 dst_sel:DWORD dst_unused:UNUSED_PAD src0_sel:WORD_1
	v_pk_mul_f32 v[164:165], v[164:165], s[84:85] op_sel_hi:[1,0]
	v_pk_mul_f32 v[166:167], v[166:167], s[84:85] op_sel_hi:[1,0]
	v_pk_fma_f32 v[104:105], v[104:105], v[136:137], v[164:165]
	v_pk_fma_f32 v[106:107], v[106:107], v[138:139], v[166:167]
	v_cvt_pk_f16_f32 v174, v104, v105
	v_cvt_pk_f16_f32 v175, v106, v107
	global_store_dwordx2 v177, v[174:175], s[80:81] offset:32
	s_waitcnt vmcnt(11)
	v_cvt_f32_f16_e32 v164, v188
	v_cvt_f32_f16_sdwa v165, v188 dst_sel:DWORD dst_unused:UNUSED_PAD src0_sel:WORD_1
	v_cvt_f32_f16_e32 v166, v189
	v_cvt_f32_f16_sdwa v167, v189 dst_sel:DWORD dst_unused:UNUSED_PAD src0_sel:WORD_1
	v_pk_mul_f32 v[164:165], v[164:165], s[84:85] op_sel_hi:[1,0]
	v_pk_mul_f32 v[166:167], v[166:167], s[84:85] op_sel_hi:[1,0]
	v_pk_fma_f32 v[108:109], v[108:109], v[140:141], v[164:165]
	v_pk_fma_f32 v[110:111], v[110:111], v[142:143], v[166:167]
	v_cvt_pk_f16_f32 v172, v108, v109
	v_cvt_pk_f16_f32 v173, v110, v111
	global_store_dwordx2 v177, v[172:173], s[80:81] offset:64
	s_waitcnt vmcnt(11)
	v_cvt_f32_f16_e32 v164, v190
	v_cvt_f32_f16_sdwa v165, v190 dst_sel:DWORD dst_unused:UNUSED_PAD src0_sel:WORD_1
	v_cvt_f32_f16_e32 v166, v191
	v_cvt_f32_f16_sdwa v167, v191 dst_sel:DWORD dst_unused:UNUSED_PAD src0_sel:WORD_1
	v_pk_mul_f32 v[164:165], v[164:165], s[84:85] op_sel_hi:[1,0]
	v_pk_mul_f32 v[166:167], v[166:167], s[84:85] op_sel_hi:[1,0]
	v_pk_fma_f32 v[112:113], v[112:113], v[144:145], v[164:165]
	v_pk_fma_f32 v[114:115], v[114:115], v[146:147], v[166:167]
	v_cvt_pk_f16_f32 v174, v112, v113
	v_cvt_pk_f16_f32 v175, v114, v115
	global_store_dwordx2 v177, v[174:175], s[80:81] offset:96
	v_add_u32_e32 v177, 0x8000, v177
	s_waitcnt vmcnt(7)
	v_cvt_f32_f16_e32 v164, v238
	v_cvt_f32_f16_sdwa v165, v238 dst_sel:DWORD dst_unused:UNUSED_PAD src0_sel:WORD_1
	v_cvt_f32_f16_e32 v166, v239
	v_cvt_f32_f16_sdwa v167, v239 dst_sel:DWORD dst_unused:UNUSED_PAD src0_sel:WORD_1
	v_pk_mul_f32 v[164:165], v[164:165], s[84:85] op_sel_hi:[1,0]
	v_pk_mul_f32 v[166:167], v[166:167], s[84:85] op_sel_hi:[1,0]
	v_pk_fma_f32 v[116:117], v[116:117], v[132:133], v[164:165]
	v_pk_fma_f32 v[118:119], v[118:119], v[134:135], v[166:167]
	v_cvt_pk_f16_f32 v172, v116, v117
	v_cvt_pk_f16_f32 v173, v118, v119
	global_store_dwordx2 v177, v[172:173], s[80:81]
	s_waitcnt vmcnt(7)
	v_cvt_f32_f16_e32 v164, v240
	v_cvt_f32_f16_sdwa v165, v240 dst_sel:DWORD dst_unused:UNUSED_PAD src0_sel:WORD_1
	v_cvt_f32_f16_e32 v166, v241
	v_cvt_f32_f16_sdwa v167, v241 dst_sel:DWORD dst_unused:UNUSED_PAD src0_sel:WORD_1
	v_pk_mul_f32 v[164:165], v[164:165], s[84:85] op_sel_hi:[1,0]
	v_pk_mul_f32 v[166:167], v[166:167], s[84:85] op_sel_hi:[1,0]
	v_pk_fma_f32 v[120:121], v[120:121], v[136:137], v[164:165]
	v_pk_fma_f32 v[122:123], v[122:123], v[138:139], v[166:167]
	v_cvt_pk_f16_f32 v174, v120, v121
	v_cvt_pk_f16_f32 v175, v122, v123
	global_store_dwordx2 v177, v[174:175], s[80:81] offset:32
	s_waitcnt vmcnt(7)
	v_cvt_f32_f16_e32 v164, v242
	v_cvt_f32_f16_sdwa v165, v242 dst_sel:DWORD dst_unused:UNUSED_PAD src0_sel:WORD_1
	v_cvt_f32_f16_e32 v166, v243
	v_cvt_f32_f16_sdwa v167, v243 dst_sel:DWORD dst_unused:UNUSED_PAD src0_sel:WORD_1
	v_pk_mul_f32 v[164:165], v[164:165], s[84:85] op_sel_hi:[1,0]
	v_pk_mul_f32 v[166:167], v[166:167], s[84:85] op_sel_hi:[1,0]
	v_pk_fma_f32 v[124:125], v[124:125], v[140:141], v[164:165]
	v_pk_fma_f32 v[126:127], v[126:127], v[142:143], v[166:167]
	v_cvt_pk_f16_f32 v172, v124, v125
	v_cvt_pk_f16_f32 v173, v126, v127
	global_store_dwordx2 v177, v[172:173], s[80:81] offset:64
	s_waitcnt vmcnt(7)
	v_cvt_f32_f16_e32 v164, v244
	v_cvt_f32_f16_sdwa v165, v244 dst_sel:DWORD dst_unused:UNUSED_PAD src0_sel:WORD_1
	v_cvt_f32_f16_e32 v166, v245
	v_cvt_f32_f16_sdwa v167, v245 dst_sel:DWORD dst_unused:UNUSED_PAD src0_sel:WORD_1
	v_pk_mul_f32 v[164:165], v[164:165], s[84:85] op_sel_hi:[1,0]
	v_pk_mul_f32 v[166:167], v[166:167], s[84:85] op_sel_hi:[1,0]
	v_pk_fma_f32 v[128:129], v[128:129], v[144:145], v[164:165]
	v_pk_fma_f32 v[130:131], v[130:131], v[146:147], v[166:167]
	v_cvt_pk_f16_f32 v174, v128, v129
	v_cvt_pk_f16_f32 v175, v130, v131
	global_store_dwordx2 v177, v[174:175], s[80:81] offset:96
	s_nop 1
	s_branch .LBB0_759
